# z1 GEMM loses its 17th (misc) column tile: tile list compacted to 1088; the 80 misc columns come from a hand-written register-only MFMA routine (32-row units, waves 0-2) before the phase barrier
# speedup vs baseline: 1.0094x; 1.0038x over previous
.LBB0_54:
	s_load_dwordx2 s[22:23], s[0:1], 0x118
	s_load_dwordx4 s[4:7], s[0:1], 0xf8
	s_waitcnt lgkmcnt(0)
	s_mov_b32 s5, s86
	s_lshl_b32 s26, s21, 3
	s_load_dword s4, s[0:1], 0x110
	s_mov_b32 s33, s22
	s_mov_b64 s[2:3], s[6:7]
	s_add_u32 s2, s2, 0xd723c00
	s_addc_u32 s3, s3, 0
	v_writelane_b32 v252, s2, 6
	s_cmpk_lt_i32 s33, 0x41
	s_mov_b32 s25, 0
	v_writelane_b32 v252, s3, 7
	s_cselect_b64 s[2:3], -1, 0
	v_writelane_b32 v252, s2, 8
	s_lshl_b32 s28, s33, 3
	s_lshl_b32 s30, s33, 9
	v_writelane_b32 v252, s3, 9
	s_add_u32 s2, s70, 0x200
	s_addc_u32 s3, s71, 0
	v_writelane_b32 v252, s2, 10
	v_mov_b32_e32 v161, 0
	v_mov_b32_e32 v191, 0x358637bd
	v_writelane_b32 v252, s3, 11
	s_add_u32 s2, s70, 0x1000
	s_addc_u32 s3, s71, 0
	v_writelane_b32 v252, s2, 12
	v_mov_b32_e32 v193, 0x3ecc95a3
	v_mov_b32_e32 v194, 0x3ca908c9
	v_writelane_b32 v252, s3, 13
	s_add_u32 s2, s70, 0x1100
	s_addc_u32 s3, s71, 0
	v_writelane_b32 v252, s2, 14
	v_mov_b32_e32 v163, 0xbdd53b94
	v_mov_b32_e32 v218, 0xffffce40
	v_writelane_b32 v252, s3, 15
	s_add_u32 s2, s70, 0x1200
	s_addc_u32 s3, s71, 0
	v_writelane_b32 v252, s2, 16
	v_mov_b32_e32 v219, 0xffffcc40
	v_mov_b32_e32 v220, 0xffffc840
	v_writelane_b32 v252, s3, 17
	s_add_u32 s2, s70, 0x1300
	s_addc_u32 s3, s71, 0
	v_writelane_b32 v252, s2, 18
	s_cmp_eq_u32 s20, 15
	v_mov_b32_e32 v221, 0xffffc440
	v_writelane_b32 v252, s3, 19
	s_cselect_b64 s[2:3], -1, 0
	v_writelane_b32 v252, s2, 20
	s_cmp_eq_u32 s20, 14
	v_mov_b32_e32 v222, 0xffffc040
	v_writelane_b32 v252, s3, 21
	s_cselect_b64 s[2:3], -1, 0
	v_writelane_b32 v252, s2, 22
	s_cmp_eq_u32 s20, 13
	v_mov_b32_e32 v223, 0xffffb840
	v_writelane_b32 v252, s3, 23
	s_cselect_b64 s[2:3], -1, 0
	v_writelane_b32 v252, s2, 24
	s_cmp_eq_u32 s20, 12
	v_mov_b32_e32 v224, 0xffff9840
	v_writelane_b32 v252, s3, 25
	s_cselect_b64 s[2:3], -1, 0
	v_writelane_b32 v252, s2, 26
	s_cmp_eq_u32 s20, 11
	v_mov_b64_e32 v[164:165], 0x198
	v_writelane_b32 v252, s3, 27
	s_cselect_b64 s[2:3], -1, 0
	v_writelane_b32 v252, s2, 28
	s_cmp_eq_u32 s20, 10
	v_mov_b64_e32 v[166:167], 0x197
	v_writelane_b32 v252, s3, 29
	s_cselect_b64 s[2:3], -1, 0
	v_writelane_b32 v252, s2, 30
	s_cmp_eq_u32 s20, 9
	v_mov_b32_e32 v228, 0x4000
	v_writelane_b32 v252, s3, 31
	s_cselect_b64 s[2:3], -1, 0
	v_writelane_b32 v252, s2, 32
	s_cmp_eq_u32 s20, 8
	v_mov_b32_e32 v229, 0xffffff00
	v_writelane_b32 v252, s3, 33
	s_cselect_b64 s[2:3], -1, 0
	v_writelane_b32 v252, s2, 34
	s_cmp_eq_u32 s20, 7
	v_mov_b32_e32 v231, 0x7f800000
	v_writelane_b32 v252, s3, 35
	s_cselect_b64 s[2:3], -1, 0
	v_writelane_b32 v252, s2, 36
	s_cmp_eq_u32 s20, 6
	v_mov_b32_e32 v232, 0x7fc00000
	v_writelane_b32 v252, s3, 37
	s_cselect_b64 s[2:3], -1, 0
	v_writelane_b32 v252, s2, 38
	s_cmp_eq_u32 s20, 5
	v_mov_b32_e32 v233, 0xff800000
	v_writelane_b32 v252, s3, 39
	s_cselect_b64 s[2:3], -1, 0
	v_writelane_b32 v252, s2, 40
	s_cmp_eq_u32 s20, 4
	v_mov_b64_e32 v[168:169], 0x110
	v_writelane_b32 v252, s3, 41
	s_cselect_b64 s[2:3], -1, 0
	v_writelane_b32 v252, s2, 42
	s_cmp_eq_u32 s20, 3
	v_mov_b64_e32 v[170:171], 0x10f
	v_writelane_b32 v252, s3, 43
	s_cselect_b64 s[2:3], -1, 0
	v_writelane_b32 v252, s2, 44
	s_cmp_eq_u32 s20, 2
	s_movk_i32 s91, 0x110
	v_writelane_b32 v252, s3, 45
	s_cselect_b64 s[2:3], -1, 0
	v_writelane_b32 v252, s2, 46
	s_cmp_eq_u32 s20, 1
	s_movk_i32 s95, 0x3ff
	v_writelane_b32 v252, s3, 47
	s_cselect_b64 s[2:3], -1, 0
	v_writelane_b32 v252, s2, 48
	s_cmp_eq_u32 s20, 0
	s_movk_i32 s90, 0x7ff
	v_writelane_b32 v252, s3, 49
	s_cselect_b64 s[2:3], -1, 0
	v_writelane_b32 v252, s2, 50
	s_movk_i32 s87, 0x100
	s_movk_i32 s76, 0x7000
	v_writelane_b32 v252, s3, 51
	s_lshl_b32 s2, s20, 8
	s_add_u32 s2, s70, s2
	s_addc_u32 s3, s71, 0
	s_add_u32 s6, s2, 0x1400
	s_addc_u32 s7, s3, 0
	v_writelane_b32 v252, s6, 52
	s_add_u32 s2, s2, 0x2400
	s_addc_u32 s3, s3, 0
	v_writelane_b32 v252, s7, 53
	v_writelane_b32 v252, s2, 54
	s_movk_i32 s94, 0x4400
	s_movk_i32 s77, 0x8000
	v_writelane_b32 v252, s3, 55
	s_add_u32 s2, s70, 0x3400
	s_addc_u32 s3, s71, 0
	v_writelane_b32 v252, s2, 56
	s_mov_b32 s80, 0xbfb8aa3b
	s_mov_b32 s81, 0x3f2aaaab
	v_writelane_b32 v252, s3, 57
	s_add_u32 s2, s70, 0x3500
	s_addc_u32 s3, s71, 0
	v_writelane_b32 v252, s2, 58
	s_cmpk_lt_i32 s5, 0x484
	s_mov_b32 s84, 0x3f317218
	v_writelane_b32 v252, s3, 59
	s_cselect_b64 s[2:3], -1, 0
	v_writelane_b32 v252, s2, 60
	s_mov_b32 s85, 0x7f800000
	s_mov_b32 s88, 0x33800000
	v_writelane_b32 v252, s3, 61
	s_ashr_i32 s2, s5, 31
	v_writelane_b32 v252, s2, 62
	s_lshr_b32 s2, s2, 29
	s_add_i32 s2, s5, s2
	s_ashr_i32 s11, s2, 3
	s_and_b32 s2, s2, -8
	s_sub_i32 s20, s5, s2
	s_mul_i32 s2, s20, 0x90
	s_or_b32 s6, s2, 4
	s_ashr_i32 s2, s33, 31
	s_cmpk_lt_i32 s5, 0x198
	v_writelane_b32 v252, s2, 63
	s_cselect_b64 s[2:3], -1, 0
	v_writelane_b32 v253, s2, 0
	s_waitcnt lgkmcnt(0)
	s_bitcmp1_b32 s4, 0
	s_mov_b32 s89, 0x42ddb3d7
	v_writelane_b32 v253, s3, 1
	s_cselect_b64 s[2:3], -1, 0
	v_writelane_b32 v253, s2, 2
	s_bitcmp1_b32 s4, 1
	s_mov_b64 s[78:79], 0x14744d00
	v_writelane_b32 v253, s3, 3
	s_cselect_b64 s[2:3], -1, 0
	v_writelane_b32 v253, s2, 4
	s_bitcmp1_b32 s4, 2
	s_mov_b32 s72, s25
	v_writelane_b32 v253, s3, 5
	s_cselect_b64 s[2:3], -1, 0
	v_writelane_b32 v253, s2, 6
	s_cmpk_lt_i32 s5, 0x110
	s_nop 0
	v_writelane_b32 v253, s3, 7
	s_cselect_b64 s[2:3], -1, 0
	v_writelane_b32 v253, s2, 8
	s_bitcmp0_b32 s4, 4
	s_nop 0
	v_writelane_b32 v253, s3, 9
	s_cselect_b64 s[2:3], -1, 0
	v_writelane_b32 v253, s2, 10
	s_bitcmp1_b32 s4, 3
	s_nop 0
	v_writelane_b32 v253, s3, 11
	s_cselect_b64 s[2:3], -1, 0
	v_writelane_b32 v253, s2, 12
	s_nop 1
	v_writelane_b32 v253, s3, 13
	s_not_b32 s2, s4
	s_lshr_b32 s2, s2, 1
	s_and_b32 s7, s2, 4
	s_cmp_gt_i32 s5, 31
	s_cselect_b64 s[2:3], -1, 0
	s_cmp_gt_i32 s33, 64
	v_writelane_b32 v253, s5, 14
	s_cselect_b64 s[4:5], -1, 0
	s_and_b64 s[2:3], s[4:5], s[2:3]
	v_writelane_b32 v253, s2, 15
	s_nop 1
	v_writelane_b32 v253, s3, 16
	s_max_u32 s2, s7, 1
	v_writelane_b32 v253, s2, 17
	s_sub_i32 s2, s33, 32
	s_lshl_b32 s3, s2, 3
	v_writelane_b32 v253, s3, 18
	s_lshl_b32 s24, s2, 9
	v_writelane_b32 v253, s2, 19
	s_cmp_lt_i32 s20, 4
	s_mul_i32 s2, s20, 0x91
	s_cselect_b32 s2, s2, s6
	s_add_i32 s2, s2, s11
	s_mul_i32 s2, s20, 0x88
	s_add_i32 s2, s2, s11
	s_lshr_b32 s3, s2, 7
	s_lshl_b32 s3, s3, 3
	s_add_i32 s2, s2, s3
	s_mul_hi_i32 s3, s2, 0x78787879
	s_lshr_b32 s4, s3, 31
	s_ashr_i32 s3, s3, 6
	s_add_i32 s3, s3, s4
	s_mul_i32 s4, s3, 0x88
	s_lshl_b32 s5, s3, 3
	s_sub_i32 s4, s2, s4
	s_sub_i32 s2, 0x44, s5
	s_min_u32 s6, s2, 8
	s_cmp_lt_i32 s20, 0
	s_cselect_b64 s[2:3], -1, 0
	v_writelane_b32 v253, s2, 20
	v_cvt_f32_ubyte0_e32 v1, s6
	v_cvt_f32_i32_e32 v0, s4
	v_writelane_b32 v253, s3, 21
	s_and_b64 s[2:3], s[2:3], exec
	s_cselect_b32 s2, 52, 51
	s_mul_i32 s2, s20, s2
	s_cselect_b32 s3, 35, 34
	s_add_i32 s2, s2, s11
	s_mul_hi_i32 s7, s2, 0x78787879
	s_lshr_b32 s8, s7, 31
	s_ashr_i32 s7, s7, 8
	s_add_i32 s7, s7, s8
	s_mul_hi_i32 s8, s2, 0x2aaaaaab
	s_lshr_b32 s9, s8, 31
	s_ashr_i32 s8, s8, 3
	s_add_i32 s8, s8, s9
	s_mul_i32 s9, s7, 0x220
	s_mul_i32 s10, s8, 48
	s_sub_i32 s9, s2, s9
	s_sub_i32 s10, s2, s10
	s_mul_i32 s2, s20, s3
	s_add_i32 s2, s2, s11
	s_mul_hi_i32 s3, s2, 0x78787879
	v_writelane_b32 v253, s11, 22
	s_lshr_b32 s11, s3, 31
	s_ashr_i32 s3, s3, 8
	s_add_i32 s3, s3, s11
	s_ashr_i32 s11, s2, 31
	s_lshr_b32 s11, s11, 27
	s_add_i32 s11, s2, s11
	s_and_b32 s12, s11, 0xffffffe0
	s_mul_i32 s13, s3, 0x220
	s_lshl_b32 s7, s7, 3
	s_sub_i32 s12, s2, s12
	s_sub_i32 s13, s2, s13
	s_sub_i32 s2, 6, s7
	s_lshl_b32 s8, s8, 3
	s_min_u32 s14, s2, 8
	s_sub_i32 s2, 0x44, s8
	v_rcp_iflag_f32_e32 v2, v1
	s_min_u32 s15, s2, 8
	s_ashr_i32 s2, s11, 5
	s_lshl_b32 s11, s2, 3
	s_sub_i32 s2, 0x44, s11
	s_lshl_b32 s17, s3, 3
	s_min_u32 s16, s2, 8
	s_sub_i32 s2, 4, s17
	v_mul_f32_e32 v2, v0, v2
	s_min_u32 s18, s2, 8
	s_ashr_i32 s2, s4, 30
	v_trunc_f32_e32 v2, v2
	s_or_b32 s19, s2, 1
	v_fma_f32 v0, -v2, v1, v0
	v_writelane_b32 v253, s20, 23
	s_lshr_b32 s2, s20, 31
	v_writelane_b32 v253, s2, 24
	v_cmp_ge_f32_e64 s[2:3], |v0|, v1
	v_cvt_i32_f32_e32 v0, v2
	s_and_b64 s[2:3], s[2:3], exec
	v_cvt_f32_ubyte0_e32 v1, s14
	s_cselect_b32 s2, s19, 0
	v_readfirstlane_b32 s3, v0
	v_cvt_f32_i32_e32 v0, s9
	v_rcp_iflag_f32_e32 v2, v1
	s_add_i32 s19, s3, s2
	s_mul_i32 s2, s19, s6
	s_sub_i32 s2, s4, s2
	s_sext_i32_i16 s2, s2
	v_mul_f32_e32 v2, v0, v2
	s_add_i32 s2, s5, s2
	v_trunc_f32_e32 v2, v2
	v_writelane_b32 v253, s2, 25
	s_ashr_i32 s2, s9, 30
	v_fma_f32 v0, -v2, v1, v0
	s_or_b32 s4, s2, 1
	v_cmp_ge_f32_e64 s[2:3], |v0|, v1
	v_cvt_i32_f32_e32 v0, v2
	s_and_b64 s[2:3], s[2:3], exec
	s_cselect_b32 s2, s4, 0
	v_cvt_f32_ubyte0_e32 v1, s15
	v_readfirstlane_b32 s3, v0
	s_add_i32 s2, s3, s2
	s_mul_i32 s3, s2, s14
	s_sub_i32 s3, s9, s3
	s_sext_i32_i16 s3, s3
	v_cvt_f32_i32_e32 v0, s10
	v_rcp_iflag_f32_e32 v2, v1
	s_bfe_i64 s[4:5], s[2:3], 0x100000
	s_lshl_b64 s[4:5], s[4:5], 20
	s_add_i32 s6, s7, s3
	v_writelane_b32 v253, s4, 26
	s_ashr_i32 s7, s6, 31
	v_mul_f32_e32 v2, v0, v2
	v_writelane_b32 v253, s5, 27
	s_mov_b32 s4, s6
	v_writelane_b32 v253, s4, 28
	v_trunc_f32_e32 v2, v2
	v_fma_f32 v0, -v2, v1, v0
	v_writelane_b32 v253, s5, 29
	s_lshl_b64 s[4:5], s[6:7], 20
	v_writelane_b32 v253, s4, 30
	s_ashr_i32 s3, s10, 30
	s_or_b32 s3, s3, 1
	v_writelane_b32 v253, s5, 31
	v_cmp_ge_f32_e64 s[4:5], |v0|, v1
	v_cvt_i32_f32_e32 v0, v2
	s_and_b64 s[4:5], s[4:5], exec
	s_cselect_b32 s3, s3, 0
	v_cvt_f32_ubyte0_e32 v1, s16
	v_readfirstlane_b32 s4, v0
	s_add_i32 s4, s4, s3
	s_mul_i32 s3, s4, s15
	s_sub_i32 s3, s10, s3
	v_cvt_f32_i32_e32 v0, s12
	v_rcp_iflag_f32_e32 v2, v1
	s_bfe_i64 s[6:7], s[4:5], 0x80000
	s_sext_i32_i8 s3, s3
	s_lshl_b64 s[6:7], s[6:7], 18
	s_add_i32 s8, s8, s3
	v_writelane_b32 v253, s6, 32
	s_ashr_i32 s9, s8, 31
	v_mul_f32_e32 v2, v0, v2
	v_writelane_b32 v253, s7, 33
	s_mov_b32 s6, s8
	v_writelane_b32 v253, s6, 34
	v_trunc_f32_e32 v2, v2
	v_fma_f32 v0, -v2, v1, v0
	v_writelane_b32 v253, s7, 35
	s_lshl_b64 s[6:7], s[8:9], 21
	v_writelane_b32 v253, s6, 36
	s_ashr_i32 s3, s12, 30
	s_or_b32 s3, s3, 1
	v_writelane_b32 v253, s7, 37
	v_cmp_ge_f32_e64 s[6:7], |v0|, v1
	v_cvt_i32_f32_e32 v0, v2
	s_and_b64 s[6:7], s[6:7], exec
	s_cselect_b32 s3, s3, 0
	v_cvt_f32_ubyte0_e32 v1, s18
	v_readfirstlane_b32 s5, v0
	s_add_i32 s6, s5, s3
	s_mul_i32 s3, s6, s16
	s_sub_i32 s3, s12, s3
	v_cvt_f32_i32_e32 v0, s13
	v_rcp_iflag_f32_e32 v2, v1
	s_bfe_i64 s[8:9], s[6:7], 0x80000
	s_sext_i32_i8 s3, s3
	s_lshl_b64 s[8:9], s[8:9], 18
	s_add_i32 s10, s11, s3
	v_writelane_b32 v253, s8, 38
	s_load_dword s7, s[0:1], 0x120
	s_ashr_i32 s11, s10, 31
	v_writelane_b32 v253, s9, 39
	s_mov_b32 s8, s10
	v_mul_f32_e32 v2, v0, v2
	v_writelane_b32 v253, s8, 40
	v_trunc_f32_e32 v2, v2
	v_fma_f32 v0, -v2, v1, v0
	v_writelane_b32 v253, s9, 41
	s_lshl_b64 s[8:9], s[10:11], 21
	v_writelane_b32 v253, s8, 42
	s_mul_i32 s5, s23, s22
	s_waitcnt lgkmcnt(0)
	s_mul_i32 s5, s5, s7
	v_writelane_b32 v253, s9, 43
	v_cmp_ge_f32_e64 s[8:9], |v0|, v1
	v_cvt_i32_f32_e32 v0, v2
	s_ashr_i32 s3, s13, 30
	v_writelane_b32 v253, s5, 44
	s_sext_i32_i16 s2, s2
	s_or_b32 s3, s3, 1
	v_writelane_b32 v253, s2, 45
	s_sext_i32_i8 s2, s4
	s_and_b64 s[8:9], s[8:9], exec
	v_writelane_b32 v253, s2, 46
	s_sext_i32_i8 s2, s6
	v_writelane_b32 v253, s2, 47
	s_cselect_b32 s2, s3, 0
	v_readfirstlane_b32 s3, v0
	s_add_i32 s2, s3, s2
	s_mul_i32 s3, s2, s18
	s_sub_i32 s3, s13, s3
	s_sext_i32_i16 s4, s19
	s_sext_i32_i16 s3, s3
	v_writelane_b32 v253, s4, 48
	s_add_i32 s6, s17, s3
	s_sext_i32_i16 s3, s2
	v_writelane_b32 v253, s3, 49
	s_bfe_i64 s[2:3], s[2:3], 0x100000
	s_lshl_b64 s[2:3], s[2:3], 21
	v_writelane_b32 v253, s2, 50
	s_mov_b32 s4, s24
	s_ashr_i32 s5, s24, 31
	v_writelane_b32 v253, s3, 51
	v_writelane_b32 v253, s4, 52
	s_lshl_b32 s2, s33, 12
	s_ashr_i32 s7, s6, 31
	v_writelane_b32 v253, s5, 53
	v_writelane_b32 v253, s2, 54
	s_add_i32 s2, s2, 0xfffe0000
	v_writelane_b32 v253, s2, 55
	s_add_i32 s2, 0, 0x23fc0
	v_writelane_b32 v253, s2, 56
	s_add_i32 s2, 0, 0x23fc4
	v_writelane_b32 v253, s2, 57
	s_add_i32 s2, 0, 0x8100
	v_writelane_b32 v253, s2, 58
	s_mov_b32 s2, s6
	v_writelane_b32 v253, s2, 59
	s_ashr_i32 s31, s30, 31
	s_ashr_i32 s29, s28, 31
	v_writelane_b32 v253, s3, 60
	s_lshl_b64 s[2:3], s[6:7], 18
	v_writelane_b32 v253, s2, 61
	s_ashr_i32 s27, s26, 31
	s_mov_b64 s[12:13], -1
	v_writelane_b32 v253, s3, 62
	s_mov_b32 s2, s30
	v_writelane_b32 v253, s2, 63
	v_mbcnt_lo_u32_b32 v0, -1, 0
	v_mbcnt_hi_u32_b32 v227, -1, v0
	v_writelane_b32 v254, s3, 0
	s_lshl_b64 s[2:3], s[30:31], 2
	v_writelane_b32 v254, s2, 1
	s_mov_b64 s[20:21], 0x80
	s_mov_b64 s[22:23], 0x10000
	v_writelane_b32 v254, s3, 2
	v_writelane_b32 v254, s28, 3
	s_lshl_b64 s[2:3], s[28:29], 13
	s_nop 0
	v_writelane_b32 v254, s29, 4
	v_writelane_b32 v254, s2, 5
	s_nop 1
	v_writelane_b32 v254, s3, 6
	v_writelane_b32 v254, s26, 7
	s_lshl_b64 s[2:3], s[26:27], 13
	s_nop 0
	v_writelane_b32 v254, s27, 8
	v_writelane_b32 v254, s2, 9
	s_nop 1
	v_writelane_b32 v254, s3, 10
	s_lshl_b64 s[2:3], s[4:5], 2
	v_writelane_b32 v254, s2, 11
	s_nop 1
	v_writelane_b32 v254, s3, 12
	v_writelane_b32 v254, s86, 13
	s_branch .LBB0_58

.LBB0_233:
	s_add_i32 s50, s50, 1
	v_readlane_b32 s2, v252, 63
	s_mul_i32 s2, s50, s2
	s_mul_hi_u32 s3, s50, s33
	s_add_i32 s3, s3, s2
	s_mul_i32 s2, s50, s33
	v_readlane_b32 s5, v253, 14
	s_add_u32 s34, s2, s5
	v_readlane_b32 s2, v252, 62
	s_addc_u32 s35, s3, s2
	v_mov_b64_e32 v[0:1], 0x440
	v_cmp_lt_i64_e64 s[2:3], s[34:35], v[0:1]
	v_mov_b64_e32 v[0:1], 0x43f
	v_cmp_gt_i64_e32 vcc, s[34:35], v[0:1]
	s_cbranch_vccnz .LBB0_239
	s_and_b32 s7, s34, 7
	s_lshr_b32 s5, s34, 3
	s_mul_i32 s30, s7, 0x88
	s_add_i32 s5, s30, s5
	s_lshr_b32 s7, s5, 7
	s_lshl_b32 s7, s7, 3
	s_add_i32 s5, s5, s7
	s_mul_hi_i32 s7, s5, 0x78787879
	s_lshr_b32 s28, s7, 31
	s_ashr_i32 s7, s7, 6
	s_add_i32 s7, s7, s28
	s_lshl_b32 s29, s7, 3
	s_sub_i32 s28, 0x44, s29
	s_min_i32 s30, s28, 8
	s_abs_i32 s28, s30
	v_cvt_f32_u32_e32 v0, s28
	s_sub_i32 s34, 0, s28
	s_mulk_i32 s7, 0x88
	s_sub_i32 s5, s5, s7
	v_rcp_iflag_f32_e32 v0, v0
	s_abs_i32 s7, s5
	s_xor_b32 s31, s5, s30
	s_ashr_i32 s31, s31, 31
	v_mul_f32_e32 v0, 0x4f7ffffe, v0
	v_cvt_u32_f32_e32 v0, v0
	s_nop 0
	v_readfirstlane_b32 s35, v0
	s_mul_i32 s34, s34, s35
	s_mul_hi_u32 s34, s35, s34
	s_add_i32 s35, s35, s34
	s_mul_hi_u32 s34, s7, s35
	s_mul_i32 s35, s34, s28
	s_sub_i32 s7, s7, s35
	s_add_i32 s36, s34, 1
	s_sub_i32 s35, s7, s28
	s_cmp_ge_u32 s7, s28
	s_cselect_b32 s34, s36, s34
	s_cselect_b32 s7, s35, s7
	s_add_i32 s35, s34, 1
	s_cmp_ge_u32 s7, s28
	s_cselect_b32 s7, s35, s34
	s_xor_b32 s7, s7, s31
	s_sub_i32 s28, s7, s31
	s_mul_i32 s7, s28, s30
	s_sub_i32 s5, s5, s7
	s_add_i32 s30, s29, s5

.LBB0_359:
	s_mov_b64 exec, -1
	v_readfirstlane_b32 s4, v190
	s_lshr_b32 s4, s4, 6
	v_readlane_b32 s5, v253, 14
	s_cmp_gt_u32 s4, 2
	s_cbranch_scc1 .Lmisc_done
	s_lshl_b32 s6, s4, 8
	s_add_i32 s5, s6, s5
	s_cmpk_gt_u32 s5, 0x21f
	s_cbranch_scc1 .Lmisc_done
	s_load_dwordx2 s[2:3], s[0:1], 0x100
	v_and_b32_e32 v0, 63, v190
	v_and_b32_e32 v1, 15, v0
	v_lshrrev_b32_e32 v3, 4, v0
	v_lshlrev_b32_e32 v3, 4, v3
	v_mul_u32_u24_e32 v2, 0x140, v1
	v_add_u32_e32 v2, v2, v3
	v_lshl_add_u32 v1, v1, 12, v3
	s_waitcnt lgkmcnt(0)
	s_lshl_b32 s6, s5, 17
	s_lshr_b32 s7, s5, 15
	s_add_u32 s8, s2, s6
	s_addc_u32 s9, s3, s7
	s_add_u32 s8, s8, 0xe144d00
	s_addc_u32 s9, s9, 0
	s_add_u32 s16, s8, 0x10000
	s_addc_u32 s17, s9, 0
	s_add_u32 s18, s2, 0x1000000
	s_addc_u32 s19, s3, 0
	s_add_u32 s28, s2, 0x1010000
	s_addc_u32 s29, s3, 0
	s_add_u32 s30, s2, 0x1020000
	s_addc_u32 s31, s3, 0
	s_add_u32 s34, s2, 0x1030000
	s_addc_u32 s35, s3, 0
	s_add_u32 s36, s2, 0x1040000
	s_addc_u32 s37, s3, 0
	s_add_u32 s38, s2, 0x8884000
	s_addc_u32 s39, s3, 0
	s_mul_i32 s6, s5, 0x2800
	s_mul_hi_u32 s7, s5, 0x2800
	s_add_u32 s40, s2, s6
	s_addc_u32 s41, s3, s7
	s_add_u32 s40, s40, 0x21344d00
	s_addc_u32 s41, s41, 0
	s_add_u32 s46, s40, 0x1400
	s_addc_u32 s47, s41, 0
	v_mov_b64_e32 v[32:33], 0
	v_mov_b64_e32 v[34:35], 0
	v_mov_b64_e32 v[36:37], 0
	v_mov_b64_e32 v[38:39], 0
	v_mov_b64_e32 v[40:41], 0
	v_mov_b64_e32 v[42:43], 0
	v_mov_b64_e32 v[44:45], 0
	v_mov_b64_e32 v[46:47], 0
	v_mov_b64_e32 v[48:49], 0
	v_mov_b64_e32 v[50:51], 0
	v_mov_b64_e32 v[52:53], 0
	v_mov_b64_e32 v[54:55], 0
	v_mov_b64_e32 v[56:57], 0
	v_mov_b64_e32 v[58:59], 0
	v_mov_b64_e32 v[60:61], 0
	v_mov_b64_e32 v[62:63], 0
	v_mov_b64_e32 v[64:65], 0
	v_mov_b64_e32 v[66:67], 0
	v_mov_b64_e32 v[68:69], 0
	v_mov_b64_e32 v[70:71], 0
	global_load_dwordx4 v[72:75], v1, s[8:9]
	global_load_dwordx4 v[76:79], v1, s[16:17]
	global_load_dwordx4 v[80:83], v1, s[18:19]
	global_load_dwordx4 v[84:87], v1, s[28:29]
	global_load_dwordx4 v[88:91], v1, s[30:31]
	global_load_dwordx4 v[92:95], v1, s[34:35]
	global_load_dwordx4 v[96:99], v1, s[36:37]
	global_load_dwordx4 v[100:103], v1, s[8:9] offset:64
	global_load_dwordx4 v[104:107], v1, s[16:17] offset:64
	global_load_dwordx4 v[108:111], v1, s[18:19] offset:64
	global_load_dwordx4 v[112:115], v1, s[28:29] offset:64
	global_load_dwordx4 v[116:119], v1, s[30:31] offset:64
	global_load_dwordx4 v[120:123], v1, s[34:35] offset:64
	global_load_dwordx4 v[124:127], v1, s[36:37] offset:64
	global_load_dwordx4 v[128:131], v1, s[8:9] offset:128
	global_load_dwordx4 v[132:135], v1, s[16:17] offset:128
	global_load_dwordx4 v[136:139], v1, s[18:19] offset:128
	global_load_dwordx4 v[140:143], v1, s[28:29] offset:128
	global_load_dwordx4 v[144:147], v1, s[30:31] offset:128
	global_load_dwordx4 v[148:151], v1, s[34:35] offset:128
	global_load_dwordx4 v[152:155], v1, s[36:37] offset:128
	global_load_dwordx4 v[156:159], v1, s[8:9] offset:192
	global_load_dwordx4 v[172:175], v1, s[16:17] offset:192
	global_load_dwordx4 v[176:179], v1, s[18:19] offset:192
	global_load_dwordx4 v[180:183], v1, s[28:29] offset:192
	global_load_dwordx4 v[184:187], v1, s[30:31] offset:192
	global_load_dwordx4 v[196:199], v1, s[34:35] offset:192
	global_load_dwordx4 v[200:203], v1, s[36:37] offset:192
	global_load_dwordx4 v[204:207], v1, s[8:9] offset:256
	global_load_dwordx4 v[208:211], v1, s[16:17] offset:256
	global_load_dwordx4 v[212:215], v1, s[18:19] offset:256
	global_load_dwordx4 v[234:237], v1, s[28:29] offset:256
	global_load_dwordx4 v[238:241], v1, s[30:31] offset:256
	global_load_dwordx4 v[242:245], v1, s[34:35] offset:256
	global_load_dwordx4 v[246:249], v1, s[36:37] offset:256
	s_waitcnt vmcnt(28)
	v_mfma_f32_16x16x32_bf16 v[32:35], v[80:83], v[72:75], v[32:35]
	v_mfma_f32_16x16x32_bf16 v[52:55], v[80:83], v[76:79], v[52:55]
	v_mfma_f32_16x16x32_bf16 v[36:39], v[84:87], v[72:75], v[36:39]
	v_mfma_f32_16x16x32_bf16 v[56:59], v[84:87], v[76:79], v[56:59]
	v_mfma_f32_16x16x32_bf16 v[40:43], v[88:91], v[72:75], v[40:43]
	v_mfma_f32_16x16x32_bf16 v[60:63], v[88:91], v[76:79], v[60:63]
	v_mfma_f32_16x16x32_bf16 v[44:47], v[92:95], v[72:75], v[44:47]
	v_mfma_f32_16x16x32_bf16 v[64:67], v[92:95], v[76:79], v[64:67]
	v_mfma_f32_16x16x32_bf16 v[48:51], v[96:99], v[72:75], v[48:51]
	v_mfma_f32_16x16x32_bf16 v[68:71], v[96:99], v[76:79], v[68:71]
	global_load_dwordx4 v[72:75], v1, s[8:9] offset:320
	global_load_dwordx4 v[76:79], v1, s[16:17] offset:320
	global_load_dwordx4 v[80:83], v1, s[18:19] offset:320
	global_load_dwordx4 v[84:87], v1, s[28:29] offset:320
	global_load_dwordx4 v[88:91], v1, s[30:31] offset:320
	global_load_dwordx4 v[92:95], v1, s[34:35] offset:320
	global_load_dwordx4 v[96:99], v1, s[36:37] offset:320
	s_waitcnt vmcnt(28)
	v_mfma_f32_16x16x32_bf16 v[32:35], v[108:111], v[100:103], v[32:35]
	v_mfma_f32_16x16x32_bf16 v[52:55], v[108:111], v[104:107], v[52:55]
	v_mfma_f32_16x16x32_bf16 v[36:39], v[112:115], v[100:103], v[36:39]
	v_mfma_f32_16x16x32_bf16 v[56:59], v[112:115], v[104:107], v[56:59]
	v_mfma_f32_16x16x32_bf16 v[40:43], v[116:119], v[100:103], v[40:43]
	v_mfma_f32_16x16x32_bf16 v[60:63], v[116:119], v[104:107], v[60:63]
	v_mfma_f32_16x16x32_bf16 v[44:47], v[120:123], v[100:103], v[44:47]
	v_mfma_f32_16x16x32_bf16 v[64:67], v[120:123], v[104:107], v[64:67]
	v_mfma_f32_16x16x32_bf16 v[48:51], v[124:127], v[100:103], v[48:51]
	v_mfma_f32_16x16x32_bf16 v[68:71], v[124:127], v[104:107], v[68:71]
	global_load_dwordx4 v[100:103], v1, s[8:9] offset:384
	global_load_dwordx4 v[104:107], v1, s[16:17] offset:384
	global_load_dwordx4 v[108:111], v1, s[18:19] offset:384
	global_load_dwordx4 v[112:115], v1, s[28:29] offset:384
	global_load_dwordx4 v[116:119], v1, s[30:31] offset:384
	global_load_dwordx4 v[120:123], v1, s[34:35] offset:384
	global_load_dwordx4 v[124:127], v1, s[36:37] offset:384
	s_waitcnt vmcnt(28)
	v_mfma_f32_16x16x32_bf16 v[32:35], v[136:139], v[128:131], v[32:35]
	v_mfma_f32_16x16x32_bf16 v[52:55], v[136:139], v[132:135], v[52:55]
	v_mfma_f32_16x16x32_bf16 v[36:39], v[140:143], v[128:131], v[36:39]
	v_mfma_f32_16x16x32_bf16 v[56:59], v[140:143], v[132:135], v[56:59]
	v_mfma_f32_16x16x32_bf16 v[40:43], v[144:147], v[128:131], v[40:43]
	v_mfma_f32_16x16x32_bf16 v[60:63], v[144:147], v[132:135], v[60:63]
	v_mfma_f32_16x16x32_bf16 v[44:47], v[148:151], v[128:131], v[44:47]
	v_mfma_f32_16x16x32_bf16 v[64:67], v[148:151], v[132:135], v[64:67]
	v_mfma_f32_16x16x32_bf16 v[48:51], v[152:155], v[128:131], v[48:51]
	v_mfma_f32_16x16x32_bf16 v[68:71], v[152:155], v[132:135], v[68:71]
	global_load_dwordx4 v[128:131], v1, s[8:9] offset:448
	global_load_dwordx4 v[132:135], v1, s[16:17] offset:448
	global_load_dwordx4 v[136:139], v1, s[18:19] offset:448
	global_load_dwordx4 v[140:143], v1, s[28:29] offset:448
	global_load_dwordx4 v[144:147], v1, s[30:31] offset:448
	global_load_dwordx4 v[148:151], v1, s[34:35] offset:448
	global_load_dwordx4 v[152:155], v1, s[36:37] offset:448
	s_waitcnt vmcnt(28)
	v_mfma_f32_16x16x32_bf16 v[32:35], v[176:179], v[156:159], v[32:35]
	v_mfma_f32_16x16x32_bf16 v[52:55], v[176:179], v[172:175], v[52:55]
	v_mfma_f32_16x16x32_bf16 v[36:39], v[180:183], v[156:159], v[36:39]
	v_mfma_f32_16x16x32_bf16 v[56:59], v[180:183], v[172:175], v[56:59]
	v_mfma_f32_16x16x32_bf16 v[40:43], v[184:187], v[156:159], v[40:43]
	v_mfma_f32_16x16x32_bf16 v[60:63], v[184:187], v[172:175], v[60:63]
	v_mfma_f32_16x16x32_bf16 v[44:47], v[196:199], v[156:159], v[44:47]
	v_mfma_f32_16x16x32_bf16 v[64:67], v[196:199], v[172:175], v[64:67]
	v_mfma_f32_16x16x32_bf16 v[48:51], v[200:203], v[156:159], v[48:51]
	v_mfma_f32_16x16x32_bf16 v[68:71], v[200:203], v[172:175], v[68:71]
	global_load_dwordx4 v[156:159], v1, s[8:9] offset:512
	global_load_dwordx4 v[172:175], v1, s[16:17] offset:512
	global_load_dwordx4 v[176:179], v1, s[18:19] offset:512
	global_load_dwordx4 v[180:183], v1, s[28:29] offset:512
	global_load_dwordx4 v[184:187], v1, s[30:31] offset:512
	global_load_dwordx4 v[196:199], v1, s[34:35] offset:512
	global_load_dwordx4 v[200:203], v1, s[36:37] offset:512
	s_waitcnt vmcnt(28)
	v_mfma_f32_16x16x32_bf16 v[32:35], v[212:215], v[204:207], v[32:35]
	v_mfma_f32_16x16x32_bf16 v[52:55], v[212:215], v[208:211], v[52:55]
	v_mfma_f32_16x16x32_bf16 v[36:39], v[234:237], v[204:207], v[36:39]
	v_mfma_f32_16x16x32_bf16 v[56:59], v[234:237], v[208:211], v[56:59]
	v_mfma_f32_16x16x32_bf16 v[40:43], v[238:241], v[204:207], v[40:43]
	v_mfma_f32_16x16x32_bf16 v[60:63], v[238:241], v[208:211], v[60:63]
	v_mfma_f32_16x16x32_bf16 v[44:47], v[242:245], v[204:207], v[44:47]
	v_mfma_f32_16x16x32_bf16 v[64:67], v[242:245], v[208:211], v[64:67]
	v_mfma_f32_16x16x32_bf16 v[48:51], v[246:249], v[204:207], v[48:51]
	v_mfma_f32_16x16x32_bf16 v[68:71], v[246:249], v[208:211], v[68:71]
	global_load_dwordx4 v[204:207], v1, s[8:9] offset:576
	global_load_dwordx4 v[208:211], v1, s[16:17] offset:576
	global_load_dwordx4 v[212:215], v1, s[18:19] offset:576
	global_load_dwordx4 v[234:237], v1, s[28:29] offset:576
	global_load_dwordx4 v[238:241], v1, s[30:31] offset:576
	global_load_dwordx4 v[242:245], v1, s[34:35] offset:576
	global_load_dwordx4 v[246:249], v1, s[36:37] offset:576
	s_waitcnt vmcnt(28)
	v_mfma_f32_16x16x32_bf16 v[32:35], v[80:83], v[72:75], v[32:35]
	v_mfma_f32_16x16x32_bf16 v[52:55], v[80:83], v[76:79], v[52:55]
	v_mfma_f32_16x16x32_bf16 v[36:39], v[84:87], v[72:75], v[36:39]
	v_mfma_f32_16x16x32_bf16 v[56:59], v[84:87], v[76:79], v[56:59]
	v_mfma_f32_16x16x32_bf16 v[40:43], v[88:91], v[72:75], v[40:43]
	v_mfma_f32_16x16x32_bf16 v[60:63], v[88:91], v[76:79], v[60:63]
	v_mfma_f32_16x16x32_bf16 v[44:47], v[92:95], v[72:75], v[44:47]
	v_mfma_f32_16x16x32_bf16 v[64:67], v[92:95], v[76:79], v[64:67]
	v_mfma_f32_16x16x32_bf16 v[48:51], v[96:99], v[72:75], v[48:51]
	v_mfma_f32_16x16x32_bf16 v[68:71], v[96:99], v[76:79], v[68:71]
	global_load_dwordx4 v[72:75], v1, s[8:9] offset:640
	global_load_dwordx4 v[76:79], v1, s[16:17] offset:640
	global_load_dwordx4 v[80:83], v1, s[18:19] offset:640
	global_load_dwordx4 v[84:87], v1, s[28:29] offset:640
	global_load_dwordx4 v[88:91], v1, s[30:31] offset:640
	global_load_dwordx4 v[92:95], v1, s[34:35] offset:640
	global_load_dwordx4 v[96:99], v1, s[36:37] offset:640
	s_waitcnt vmcnt(28)
	v_mfma_f32_16x16x32_bf16 v[32:35], v[108:111], v[100:103], v[32:35]
	v_mfma_f32_16x16x32_bf16 v[52:55], v[108:111], v[104:107], v[52:55]
	v_mfma_f32_16x16x32_bf16 v[36:39], v[112:115], v[100:103], v[36:39]
	v_mfma_f32_16x16x32_bf16 v[56:59], v[112:115], v[104:107], v[56:59]
	v_mfma_f32_16x16x32_bf16 v[40:43], v[116:119], v[100:103], v[40:43]
	v_mfma_f32_16x16x32_bf16 v[60:63], v[116:119], v[104:107], v[60:63]
	v_mfma_f32_16x16x32_bf16 v[44:47], v[120:123], v[100:103], v[44:47]
	v_mfma_f32_16x16x32_bf16 v[64:67], v[120:123], v[104:107], v[64:67]
	v_mfma_f32_16x16x32_bf16 v[48:51], v[124:127], v[100:103], v[48:51]
	v_mfma_f32_16x16x32_bf16 v[68:71], v[124:127], v[104:107], v[68:71]
	global_load_dwordx4 v[100:103], v1, s[8:9] offset:704
	global_load_dwordx4 v[104:107], v1, s[16:17] offset:704
	global_load_dwordx4 v[108:111], v1, s[18:19] offset:704
	global_load_dwordx4 v[112:115], v1, s[28:29] offset:704
	global_load_dwordx4 v[116:119], v1, s[30:31] offset:704
	global_load_dwordx4 v[120:123], v1, s[34:35] offset:704
	global_load_dwordx4 v[124:127], v1, s[36:37] offset:704
	s_waitcnt vmcnt(28)
	v_mfma_f32_16x16x32_bf16 v[32:35], v[136:139], v[128:131], v[32:35]
	v_mfma_f32_16x16x32_bf16 v[52:55], v[136:139], v[132:135], v[52:55]
	v_mfma_f32_16x16x32_bf16 v[36:39], v[140:143], v[128:131], v[36:39]
	v_mfma_f32_16x16x32_bf16 v[56:59], v[140:143], v[132:135], v[56:59]
	v_mfma_f32_16x16x32_bf16 v[40:43], v[144:147], v[128:131], v[40:43]
	v_mfma_f32_16x16x32_bf16 v[60:63], v[144:147], v[132:135], v[60:63]
	v_mfma_f32_16x16x32_bf16 v[44:47], v[148:151], v[128:131], v[44:47]
	v_mfma_f32_16x16x32_bf16 v[64:67], v[148:151], v[132:135], v[64:67]
	v_mfma_f32_16x16x32_bf16 v[48:51], v[152:155], v[128:131], v[48:51]
	v_mfma_f32_16x16x32_bf16 v[68:71], v[152:155], v[132:135], v[68:71]
	global_load_dwordx4 v[128:131], v1, s[8:9] offset:768
	global_load_dwordx4 v[132:135], v1, s[16:17] offset:768
	global_load_dwordx4 v[136:139], v1, s[18:19] offset:768
	global_load_dwordx4 v[140:143], v1, s[28:29] offset:768
	global_load_dwordx4 v[144:147], v1, s[30:31] offset:768
	global_load_dwordx4 v[148:151], v1, s[34:35] offset:768
	global_load_dwordx4 v[152:155], v1, s[36:37] offset:768
	s_waitcnt vmcnt(28)
	v_mfma_f32_16x16x32_bf16 v[32:35], v[176:179], v[156:159], v[32:35]
	v_mfma_f32_16x16x32_bf16 v[52:55], v[176:179], v[172:175], v[52:55]
	v_mfma_f32_16x16x32_bf16 v[36:39], v[180:183], v[156:159], v[36:39]
	v_mfma_f32_16x16x32_bf16 v[56:59], v[180:183], v[172:175], v[56:59]
	v_mfma_f32_16x16x32_bf16 v[40:43], v[184:187], v[156:159], v[40:43]
	v_mfma_f32_16x16x32_bf16 v[60:63], v[184:187], v[172:175], v[60:63]
	v_mfma_f32_16x16x32_bf16 v[44:47], v[196:199], v[156:159], v[44:47]
	v_mfma_f32_16x16x32_bf16 v[64:67], v[196:199], v[172:175], v[64:67]
	v_mfma_f32_16x16x32_bf16 v[48:51], v[200:203], v[156:159], v[48:51]
	v_mfma_f32_16x16x32_bf16 v[68:71], v[200:203], v[172:175], v[68:71]
	global_load_dwordx4 v[156:159], v1, s[8:9] offset:832
	global_load_dwordx4 v[172:175], v1, s[16:17] offset:832
	global_load_dwordx4 v[176:179], v1, s[18:19] offset:832
	global_load_dwordx4 v[180:183], v1, s[28:29] offset:832
	global_load_dwordx4 v[184:187], v1, s[30:31] offset:832
	global_load_dwordx4 v[196:199], v1, s[34:35] offset:832
	global_load_dwordx4 v[200:203], v1, s[36:37] offset:832
	s_waitcnt vmcnt(28)
	v_mfma_f32_16x16x32_bf16 v[32:35], v[212:215], v[204:207], v[32:35]
	v_mfma_f32_16x16x32_bf16 v[52:55], v[212:215], v[208:211], v[52:55]
	v_mfma_f32_16x16x32_bf16 v[36:39], v[234:237], v[204:207], v[36:39]
	v_mfma_f32_16x16x32_bf16 v[56:59], v[234:237], v[208:211], v[56:59]
	v_mfma_f32_16x16x32_bf16 v[40:43], v[238:241], v[204:207], v[40:43]
	v_mfma_f32_16x16x32_bf16 v[60:63], v[238:241], v[208:211], v[60:63]
	v_mfma_f32_16x16x32_bf16 v[44:47], v[242:245], v[204:207], v[44:47]
	v_mfma_f32_16x16x32_bf16 v[64:67], v[242:245], v[208:211], v[64:67]
	v_mfma_f32_16x16x32_bf16 v[48:51], v[246:249], v[204:207], v[48:51]
	v_mfma_f32_16x16x32_bf16 v[68:71], v[246:249], v[208:211], v[68:71]
	global_load_dwordx4 v[204:207], v1, s[8:9] offset:896
	global_load_dwordx4 v[208:211], v1, s[16:17] offset:896
	global_load_dwordx4 v[212:215], v1, s[18:19] offset:896
	global_load_dwordx4 v[234:237], v1, s[28:29] offset:896
	global_load_dwordx4 v[238:241], v1, s[30:31] offset:896
	global_load_dwordx4 v[242:245], v1, s[34:35] offset:896
	global_load_dwordx4 v[246:249], v1, s[36:37] offset:896
	s_waitcnt vmcnt(28)
	v_mfma_f32_16x16x32_bf16 v[32:35], v[80:83], v[72:75], v[32:35]
	v_mfma_f32_16x16x32_bf16 v[52:55], v[80:83], v[76:79], v[52:55]
	v_mfma_f32_16x16x32_bf16 v[36:39], v[84:87], v[72:75], v[36:39]
	v_mfma_f32_16x16x32_bf16 v[56:59], v[84:87], v[76:79], v[56:59]
	v_mfma_f32_16x16x32_bf16 v[40:43], v[88:91], v[72:75], v[40:43]
	v_mfma_f32_16x16x32_bf16 v[60:63], v[88:91], v[76:79], v[60:63]
	v_mfma_f32_16x16x32_bf16 v[44:47], v[92:95], v[72:75], v[44:47]
	v_mfma_f32_16x16x32_bf16 v[64:67], v[92:95], v[76:79], v[64:67]
	v_mfma_f32_16x16x32_bf16 v[48:51], v[96:99], v[72:75], v[48:51]
	v_mfma_f32_16x16x32_bf16 v[68:71], v[96:99], v[76:79], v[68:71]
	global_load_dwordx4 v[72:75], v1, s[8:9] offset:960
	global_load_dwordx4 v[76:79], v1, s[16:17] offset:960
	global_load_dwordx4 v[80:83], v1, s[18:19] offset:960
	global_load_dwordx4 v[84:87], v1, s[28:29] offset:960
	global_load_dwordx4 v[88:91], v1, s[30:31] offset:960
	global_load_dwordx4 v[92:95], v1, s[34:35] offset:960
	global_load_dwordx4 v[96:99], v1, s[36:37] offset:960
	s_waitcnt vmcnt(28)
	v_mfma_f32_16x16x32_bf16 v[32:35], v[108:111], v[100:103], v[32:35]
	v_mfma_f32_16x16x32_bf16 v[52:55], v[108:111], v[104:107], v[52:55]
	v_mfma_f32_16x16x32_bf16 v[36:39], v[112:115], v[100:103], v[36:39]
	v_mfma_f32_16x16x32_bf16 v[56:59], v[112:115], v[104:107], v[56:59]
	v_mfma_f32_16x16x32_bf16 v[40:43], v[116:119], v[100:103], v[40:43]
	v_mfma_f32_16x16x32_bf16 v[60:63], v[116:119], v[104:107], v[60:63]
	v_mfma_f32_16x16x32_bf16 v[44:47], v[120:123], v[100:103], v[44:47]
	v_mfma_f32_16x16x32_bf16 v[64:67], v[120:123], v[104:107], v[64:67]
	v_mfma_f32_16x16x32_bf16 v[48:51], v[124:127], v[100:103], v[48:51]
	v_mfma_f32_16x16x32_bf16 v[68:71], v[124:127], v[104:107], v[68:71]
	global_load_dwordx4 v[100:103], v1, s[8:9] offset:1024
	global_load_dwordx4 v[104:107], v1, s[16:17] offset:1024
	global_load_dwordx4 v[108:111], v1, s[18:19] offset:1024
	global_load_dwordx4 v[112:115], v1, s[28:29] offset:1024
	global_load_dwordx4 v[116:119], v1, s[30:31] offset:1024
	global_load_dwordx4 v[120:123], v1, s[34:35] offset:1024
	global_load_dwordx4 v[124:127], v1, s[36:37] offset:1024
	s_waitcnt vmcnt(28)
	v_mfma_f32_16x16x32_bf16 v[32:35], v[136:139], v[128:131], v[32:35]
	v_mfma_f32_16x16x32_bf16 v[52:55], v[136:139], v[132:135], v[52:55]
	v_mfma_f32_16x16x32_bf16 v[36:39], v[140:143], v[128:131], v[36:39]
	v_mfma_f32_16x16x32_bf16 v[56:59], v[140:143], v[132:135], v[56:59]
	v_mfma_f32_16x16x32_bf16 v[40:43], v[144:147], v[128:131], v[40:43]
	v_mfma_f32_16x16x32_bf16 v[60:63], v[144:147], v[132:135], v[60:63]
	v_mfma_f32_16x16x32_bf16 v[44:47], v[148:151], v[128:131], v[44:47]
	v_mfma_f32_16x16x32_bf16 v[64:67], v[148:151], v[132:135], v[64:67]
	v_mfma_f32_16x16x32_bf16 v[48:51], v[152:155], v[128:131], v[48:51]
	v_mfma_f32_16x16x32_bf16 v[68:71], v[152:155], v[132:135], v[68:71]
	global_load_dwordx4 v[128:131], v1, s[8:9] offset:1088
	global_load_dwordx4 v[132:135], v1, s[16:17] offset:1088
	global_load_dwordx4 v[136:139], v1, s[18:19] offset:1088
	global_load_dwordx4 v[140:143], v1, s[28:29] offset:1088
	global_load_dwordx4 v[144:147], v1, s[30:31] offset:1088
	global_load_dwordx4 v[148:151], v1, s[34:35] offset:1088
	global_load_dwordx4 v[152:155], v1, s[36:37] offset:1088
	s_waitcnt vmcnt(28)
	v_mfma_f32_16x16x32_bf16 v[32:35], v[176:179], v[156:159], v[32:35]
	v_mfma_f32_16x16x32_bf16 v[52:55], v[176:179], v[172:175], v[52:55]
	v_mfma_f32_16x16x32_bf16 v[36:39], v[180:183], v[156:159], v[36:39]
	v_mfma_f32_16x16x32_bf16 v[56:59], v[180:183], v[172:175], v[56:59]
	v_mfma_f32_16x16x32_bf16 v[40:43], v[184:187], v[156:159], v[40:43]
	v_mfma_f32_16x16x32_bf16 v[60:63], v[184:187], v[172:175], v[60:63]
	v_mfma_f32_16x16x32_bf16 v[44:47], v[196:199], v[156:159], v[44:47]
	v_mfma_f32_16x16x32_bf16 v[64:67], v[196:199], v[172:175], v[64:67]
	v_mfma_f32_16x16x32_bf16 v[48:51], v[200:203], v[156:159], v[48:51]
	v_mfma_f32_16x16x32_bf16 v[68:71], v[200:203], v[172:175], v[68:71]
	global_load_dwordx4 v[156:159], v1, s[8:9] offset:1152
	global_load_dwordx4 v[172:175], v1, s[16:17] offset:1152
	global_load_dwordx4 v[176:179], v1, s[18:19] offset:1152
	global_load_dwordx4 v[180:183], v1, s[28:29] offset:1152
	global_load_dwordx4 v[184:187], v1, s[30:31] offset:1152
	global_load_dwordx4 v[196:199], v1, s[34:35] offset:1152
	global_load_dwordx4 v[200:203], v1, s[36:37] offset:1152
	s_waitcnt vmcnt(28)
	v_mfma_f32_16x16x32_bf16 v[32:35], v[212:215], v[204:207], v[32:35]
	v_mfma_f32_16x16x32_bf16 v[52:55], v[212:215], v[208:211], v[52:55]
	v_mfma_f32_16x16x32_bf16 v[36:39], v[234:237], v[204:207], v[36:39]
	v_mfma_f32_16x16x32_bf16 v[56:59], v[234:237], v[208:211], v[56:59]
	v_mfma_f32_16x16x32_bf16 v[40:43], v[238:241], v[204:207], v[40:43]
	v_mfma_f32_16x16x32_bf16 v[60:63], v[238:241], v[208:211], v[60:63]
	v_mfma_f32_16x16x32_bf16 v[44:47], v[242:245], v[204:207], v[44:47]
	v_mfma_f32_16x16x32_bf16 v[64:67], v[242:245], v[208:211], v[64:67]
	v_mfma_f32_16x16x32_bf16 v[48:51], v[246:249], v[204:207], v[48:51]
	v_mfma_f32_16x16x32_bf16 v[68:71], v[246:249], v[208:211], v[68:71]
	global_load_dwordx4 v[204:207], v1, s[8:9] offset:1216
	global_load_dwordx4 v[208:211], v1, s[16:17] offset:1216
	global_load_dwordx4 v[212:215], v1, s[18:19] offset:1216
	global_load_dwordx4 v[234:237], v1, s[28:29] offset:1216
	global_load_dwordx4 v[238:241], v1, s[30:31] offset:1216
	global_load_dwordx4 v[242:245], v1, s[34:35] offset:1216
	global_load_dwordx4 v[246:249], v1, s[36:37] offset:1216
	s_waitcnt vmcnt(28)
	v_mfma_f32_16x16x32_bf16 v[32:35], v[80:83], v[72:75], v[32:35]
	v_mfma_f32_16x16x32_bf16 v[52:55], v[80:83], v[76:79], v[52:55]
	v_mfma_f32_16x16x32_bf16 v[36:39], v[84:87], v[72:75], v[36:39]
	v_mfma_f32_16x16x32_bf16 v[56:59], v[84:87], v[76:79], v[56:59]
	v_mfma_f32_16x16x32_bf16 v[40:43], v[88:91], v[72:75], v[40:43]
	v_mfma_f32_16x16x32_bf16 v[60:63], v[88:91], v[76:79], v[60:63]
	v_mfma_f32_16x16x32_bf16 v[44:47], v[92:95], v[72:75], v[44:47]
	v_mfma_f32_16x16x32_bf16 v[64:67], v[92:95], v[76:79], v[64:67]
	v_mfma_f32_16x16x32_bf16 v[48:51], v[96:99], v[72:75], v[48:51]
	v_mfma_f32_16x16x32_bf16 v[68:71], v[96:99], v[76:79], v[68:71]
	global_load_dwordx4 v[72:75], v1, s[8:9] offset:1280
	global_load_dwordx4 v[76:79], v1, s[16:17] offset:1280
	global_load_dwordx4 v[80:83], v1, s[18:19] offset:1280
	global_load_dwordx4 v[84:87], v1, s[28:29] offset:1280
	global_load_dwordx4 v[88:91], v1, s[30:31] offset:1280
	global_load_dwordx4 v[92:95], v1, s[34:35] offset:1280
	global_load_dwordx4 v[96:99], v1, s[36:37] offset:1280
	s_waitcnt vmcnt(28)
	v_mfma_f32_16x16x32_bf16 v[32:35], v[108:111], v[100:103], v[32:35]
	v_mfma_f32_16x16x32_bf16 v[52:55], v[108:111], v[104:107], v[52:55]
	v_mfma_f32_16x16x32_bf16 v[36:39], v[112:115], v[100:103], v[36:39]
	v_mfma_f32_16x16x32_bf16 v[56:59], v[112:115], v[104:107], v[56:59]
	v_mfma_f32_16x16x32_bf16 v[40:43], v[116:119], v[100:103], v[40:43]
	v_mfma_f32_16x16x32_bf16 v[60:63], v[116:119], v[104:107], v[60:63]
	v_mfma_f32_16x16x32_bf16 v[44:47], v[120:123], v[100:103], v[44:47]
	v_mfma_f32_16x16x32_bf16 v[64:67], v[120:123], v[104:107], v[64:67]
	v_mfma_f32_16x16x32_bf16 v[48:51], v[124:127], v[100:103], v[48:51]
	v_mfma_f32_16x16x32_bf16 v[68:71], v[124:127], v[104:107], v[68:71]
	global_load_dwordx4 v[100:103], v1, s[8:9] offset:1344
	global_load_dwordx4 v[104:107], v1, s[16:17] offset:1344
	global_load_dwordx4 v[108:111], v1, s[18:19] offset:1344
	global_load_dwordx4 v[112:115], v1, s[28:29] offset:1344
	global_load_dwordx4 v[116:119], v1, s[30:31] offset:1344
	global_load_dwordx4 v[120:123], v1, s[34:35] offset:1344
	global_load_dwordx4 v[124:127], v1, s[36:37] offset:1344
	s_waitcnt vmcnt(28)
	v_mfma_f32_16x16x32_bf16 v[32:35], v[136:139], v[128:131], v[32:35]
	v_mfma_f32_16x16x32_bf16 v[52:55], v[136:139], v[132:135], v[52:55]
	v_mfma_f32_16x16x32_bf16 v[36:39], v[140:143], v[128:131], v[36:39]
	v_mfma_f32_16x16x32_bf16 v[56:59], v[140:143], v[132:135], v[56:59]
	v_mfma_f32_16x16x32_bf16 v[40:43], v[144:147], v[128:131], v[40:43]
	v_mfma_f32_16x16x32_bf16 v[60:63], v[144:147], v[132:135], v[60:63]
	v_mfma_f32_16x16x32_bf16 v[44:47], v[148:151], v[128:131], v[44:47]
	v_mfma_f32_16x16x32_bf16 v[64:67], v[148:151], v[132:135], v[64:67]
	v_mfma_f32_16x16x32_bf16 v[48:51], v[152:155], v[128:131], v[48:51]
	v_mfma_f32_16x16x32_bf16 v[68:71], v[152:155], v[132:135], v[68:71]
	global_load_dwordx4 v[128:131], v1, s[8:9] offset:1408
	global_load_dwordx4 v[132:135], v1, s[16:17] offset:1408
	global_load_dwordx4 v[136:139], v1, s[18:19] offset:1408
	global_load_dwordx4 v[140:143], v1, s[28:29] offset:1408
	global_load_dwordx4 v[144:147], v1, s[30:31] offset:1408
	global_load_dwordx4 v[148:151], v1, s[34:35] offset:1408
	global_load_dwordx4 v[152:155], v1, s[36:37] offset:1408
	s_waitcnt vmcnt(28)
	v_mfma_f32_16x16x32_bf16 v[32:35], v[176:179], v[156:159], v[32:35]
	v_mfma_f32_16x16x32_bf16 v[52:55], v[176:179], v[172:175], v[52:55]
	v_mfma_f32_16x16x32_bf16 v[36:39], v[180:183], v[156:159], v[36:39]
	v_mfma_f32_16x16x32_bf16 v[56:59], v[180:183], v[172:175], v[56:59]
	v_mfma_f32_16x16x32_bf16 v[40:43], v[184:187], v[156:159], v[40:43]
	v_mfma_f32_16x16x32_bf16 v[60:63], v[184:187], v[172:175], v[60:63]
	v_mfma_f32_16x16x32_bf16 v[44:47], v[196:199], v[156:159], v[44:47]
	v_mfma_f32_16x16x32_bf16 v[64:67], v[196:199], v[172:175], v[64:67]
	v_mfma_f32_16x16x32_bf16 v[48:51], v[200:203], v[156:159], v[48:51]
	v_mfma_f32_16x16x32_bf16 v[68:71], v[200:203], v[172:175], v[68:71]
	global_load_dwordx4 v[156:159], v1, s[8:9] offset:1472
	global_load_dwordx4 v[172:175], v1, s[16:17] offset:1472
	global_load_dwordx4 v[176:179], v1, s[18:19] offset:1472
	global_load_dwordx4 v[180:183], v1, s[28:29] offset:1472
	global_load_dwordx4 v[184:187], v1, s[30:31] offset:1472
	global_load_dwordx4 v[196:199], v1, s[34:35] offset:1472
	global_load_dwordx4 v[200:203], v1, s[36:37] offset:1472
	s_waitcnt vmcnt(28)
	v_mfma_f32_16x16x32_bf16 v[32:35], v[212:215], v[204:207], v[32:35]
	v_mfma_f32_16x16x32_bf16 v[52:55], v[212:215], v[208:211], v[52:55]
	v_mfma_f32_16x16x32_bf16 v[36:39], v[234:237], v[204:207], v[36:39]
	v_mfma_f32_16x16x32_bf16 v[56:59], v[234:237], v[208:211], v[56:59]
	v_mfma_f32_16x16x32_bf16 v[40:43], v[238:241], v[204:207], v[40:43]
	v_mfma_f32_16x16x32_bf16 v[60:63], v[238:241], v[208:211], v[60:63]
	v_mfma_f32_16x16x32_bf16 v[44:47], v[242:245], v[204:207], v[44:47]
	v_mfma_f32_16x16x32_bf16 v[64:67], v[242:245], v[208:211], v[64:67]
	v_mfma_f32_16x16x32_bf16 v[48:51], v[246:249], v[204:207], v[48:51]
	v_mfma_f32_16x16x32_bf16 v[68:71], v[246:249], v[208:211], v[68:71]
	global_load_dwordx4 v[204:207], v1, s[8:9] offset:1536
	global_load_dwordx4 v[208:211], v1, s[16:17] offset:1536
	global_load_dwordx4 v[212:215], v1, s[18:19] offset:1536
	global_load_dwordx4 v[234:237], v1, s[28:29] offset:1536
	global_load_dwordx4 v[238:241], v1, s[30:31] offset:1536
	global_load_dwordx4 v[242:245], v1, s[34:35] offset:1536
	global_load_dwordx4 v[246:249], v1, s[36:37] offset:1536
	s_waitcnt vmcnt(28)
	v_mfma_f32_16x16x32_bf16 v[32:35], v[80:83], v[72:75], v[32:35]
	v_mfma_f32_16x16x32_bf16 v[52:55], v[80:83], v[76:79], v[52:55]
	v_mfma_f32_16x16x32_bf16 v[36:39], v[84:87], v[72:75], v[36:39]
	v_mfma_f32_16x16x32_bf16 v[56:59], v[84:87], v[76:79], v[56:59]
	v_mfma_f32_16x16x32_bf16 v[40:43], v[88:91], v[72:75], v[40:43]
	v_mfma_f32_16x16x32_bf16 v[60:63], v[88:91], v[76:79], v[60:63]
	v_mfma_f32_16x16x32_bf16 v[44:47], v[92:95], v[72:75], v[44:47]
	v_mfma_f32_16x16x32_bf16 v[64:67], v[92:95], v[76:79], v[64:67]
	v_mfma_f32_16x16x32_bf16 v[48:51], v[96:99], v[72:75], v[48:51]
	v_mfma_f32_16x16x32_bf16 v[68:71], v[96:99], v[76:79], v[68:71]
	global_load_dwordx4 v[72:75], v1, s[8:9] offset:1600
	global_load_dwordx4 v[76:79], v1, s[16:17] offset:1600
	global_load_dwordx4 v[80:83], v1, s[18:19] offset:1600
	global_load_dwordx4 v[84:87], v1, s[28:29] offset:1600
	global_load_dwordx4 v[88:91], v1, s[30:31] offset:1600
	global_load_dwordx4 v[92:95], v1, s[34:35] offset:1600
	global_load_dwordx4 v[96:99], v1, s[36:37] offset:1600
	s_waitcnt vmcnt(28)
	v_mfma_f32_16x16x32_bf16 v[32:35], v[108:111], v[100:103], v[32:35]
	v_mfma_f32_16x16x32_bf16 v[52:55], v[108:111], v[104:107], v[52:55]
	v_mfma_f32_16x16x32_bf16 v[36:39], v[112:115], v[100:103], v[36:39]
	v_mfma_f32_16x16x32_bf16 v[56:59], v[112:115], v[104:107], v[56:59]
	v_mfma_f32_16x16x32_bf16 v[40:43], v[116:119], v[100:103], v[40:43]
	v_mfma_f32_16x16x32_bf16 v[60:63], v[116:119], v[104:107], v[60:63]
	v_mfma_f32_16x16x32_bf16 v[44:47], v[120:123], v[100:103], v[44:47]
	v_mfma_f32_16x16x32_bf16 v[64:67], v[120:123], v[104:107], v[64:67]
	v_mfma_f32_16x16x32_bf16 v[48:51], v[124:127], v[100:103], v[48:51]
	v_mfma_f32_16x16x32_bf16 v[68:71], v[124:127], v[104:107], v[68:71]
	global_load_dwordx4 v[100:103], v1, s[8:9] offset:1664
	global_load_dwordx4 v[104:107], v1, s[16:17] offset:1664
	global_load_dwordx4 v[108:111], v1, s[18:19] offset:1664
	global_load_dwordx4 v[112:115], v1, s[28:29] offset:1664
	global_load_dwordx4 v[116:119], v1, s[30:31] offset:1664
	global_load_dwordx4 v[120:123], v1, s[34:35] offset:1664
	global_load_dwordx4 v[124:127], v1, s[36:37] offset:1664
	s_waitcnt vmcnt(28)
	v_mfma_f32_16x16x32_bf16 v[32:35], v[136:139], v[128:131], v[32:35]
	v_mfma_f32_16x16x32_bf16 v[52:55], v[136:139], v[132:135], v[52:55]
	v_mfma_f32_16x16x32_bf16 v[36:39], v[140:143], v[128:131], v[36:39]
	v_mfma_f32_16x16x32_bf16 v[56:59], v[140:143], v[132:135], v[56:59]
	v_mfma_f32_16x16x32_bf16 v[40:43], v[144:147], v[128:131], v[40:43]
	v_mfma_f32_16x16x32_bf16 v[60:63], v[144:147], v[132:135], v[60:63]
	v_mfma_f32_16x16x32_bf16 v[44:47], v[148:151], v[128:131], v[44:47]
	v_mfma_f32_16x16x32_bf16 v[64:67], v[148:151], v[132:135], v[64:67]
	v_mfma_f32_16x16x32_bf16 v[48:51], v[152:155], v[128:131], v[48:51]
	v_mfma_f32_16x16x32_bf16 v[68:71], v[152:155], v[132:135], v[68:71]
	global_load_dwordx4 v[128:131], v1, s[8:9] offset:1728
	global_load_dwordx4 v[132:135], v1, s[16:17] offset:1728
	global_load_dwordx4 v[136:139], v1, s[18:19] offset:1728
	global_load_dwordx4 v[140:143], v1, s[28:29] offset:1728
	global_load_dwordx4 v[144:147], v1, s[30:31] offset:1728
	global_load_dwordx4 v[148:151], v1, s[34:35] offset:1728
	global_load_dwordx4 v[152:155], v1, s[36:37] offset:1728
	s_waitcnt vmcnt(28)
	v_mfma_f32_16x16x32_bf16 v[32:35], v[176:179], v[156:159], v[32:35]
	v_mfma_f32_16x16x32_bf16 v[52:55], v[176:179], v[172:175], v[52:55]
	v_mfma_f32_16x16x32_bf16 v[36:39], v[180:183], v[156:159], v[36:39]
	v_mfma_f32_16x16x32_bf16 v[56:59], v[180:183], v[172:175], v[56:59]
	v_mfma_f32_16x16x32_bf16 v[40:43], v[184:187], v[156:159], v[40:43]
	v_mfma_f32_16x16x32_bf16 v[60:63], v[184:187], v[172:175], v[60:63]
	v_mfma_f32_16x16x32_bf16 v[44:47], v[196:199], v[156:159], v[44:47]
	v_mfma_f32_16x16x32_bf16 v[64:67], v[196:199], v[172:175], v[64:67]
	v_mfma_f32_16x16x32_bf16 v[48:51], v[200:203], v[156:159], v[48:51]
	v_mfma_f32_16x16x32_bf16 v[68:71], v[200:203], v[172:175], v[68:71]
	global_load_dwordx4 v[156:159], v1, s[8:9] offset:1792
	global_load_dwordx4 v[172:175], v1, s[16:17] offset:1792
	global_load_dwordx4 v[176:179], v1, s[18:19] offset:1792
	global_load_dwordx4 v[180:183], v1, s[28:29] offset:1792
	global_load_dwordx4 v[184:187], v1, s[30:31] offset:1792
	global_load_dwordx4 v[196:199], v1, s[34:35] offset:1792
	global_load_dwordx4 v[200:203], v1, s[36:37] offset:1792
	s_waitcnt vmcnt(28)
	v_mfma_f32_16x16x32_bf16 v[32:35], v[212:215], v[204:207], v[32:35]
	v_mfma_f32_16x16x32_bf16 v[52:55], v[212:215], v[208:211], v[52:55]
	v_mfma_f32_16x16x32_bf16 v[36:39], v[234:237], v[204:207], v[36:39]
	v_mfma_f32_16x16x32_bf16 v[56:59], v[234:237], v[208:211], v[56:59]
	v_mfma_f32_16x16x32_bf16 v[40:43], v[238:241], v[204:207], v[40:43]
	v_mfma_f32_16x16x32_bf16 v[60:63], v[238:241], v[208:211], v[60:63]
	v_mfma_f32_16x16x32_bf16 v[44:47], v[242:245], v[204:207], v[44:47]
	v_mfma_f32_16x16x32_bf16 v[64:67], v[242:245], v[208:211], v[64:67]
	v_mfma_f32_16x16x32_bf16 v[48:51], v[246:249], v[204:207], v[48:51]
	v_mfma_f32_16x16x32_bf16 v[68:71], v[246:249], v[208:211], v[68:71]
	global_load_dwordx4 v[204:207], v1, s[8:9] offset:1856
	global_load_dwordx4 v[208:211], v1, s[16:17] offset:1856
	global_load_dwordx4 v[212:215], v1, s[18:19] offset:1856
	global_load_dwordx4 v[234:237], v1, s[28:29] offset:1856
	global_load_dwordx4 v[238:241], v1, s[30:31] offset:1856
	global_load_dwordx4 v[242:245], v1, s[34:35] offset:1856
	global_load_dwordx4 v[246:249], v1, s[36:37] offset:1856
	s_waitcnt vmcnt(28)
	v_mfma_f32_16x16x32_bf16 v[32:35], v[80:83], v[72:75], v[32:35]
	v_mfma_f32_16x16x32_bf16 v[52:55], v[80:83], v[76:79], v[52:55]
	v_mfma_f32_16x16x32_bf16 v[36:39], v[84:87], v[72:75], v[36:39]
	v_mfma_f32_16x16x32_bf16 v[56:59], v[84:87], v[76:79], v[56:59]
	v_mfma_f32_16x16x32_bf16 v[40:43], v[88:91], v[72:75], v[40:43]
	v_mfma_f32_16x16x32_bf16 v[60:63], v[88:91], v[76:79], v[60:63]
	v_mfma_f32_16x16x32_bf16 v[44:47], v[92:95], v[72:75], v[44:47]
	v_mfma_f32_16x16x32_bf16 v[64:67], v[92:95], v[76:79], v[64:67]
	v_mfma_f32_16x16x32_bf16 v[48:51], v[96:99], v[72:75], v[48:51]
	v_mfma_f32_16x16x32_bf16 v[68:71], v[96:99], v[76:79], v[68:71]
	global_load_dwordx4 v[72:75], v1, s[8:9] offset:1920
	global_load_dwordx4 v[76:79], v1, s[16:17] offset:1920
	global_load_dwordx4 v[80:83], v1, s[18:19] offset:1920
	global_load_dwordx4 v[84:87], v1, s[28:29] offset:1920
	global_load_dwordx4 v[88:91], v1, s[30:31] offset:1920
	global_load_dwordx4 v[92:95], v1, s[34:35] offset:1920
	global_load_dwordx4 v[96:99], v1, s[36:37] offset:1920
	s_waitcnt vmcnt(28)
	v_mfma_f32_16x16x32_bf16 v[32:35], v[108:111], v[100:103], v[32:35]
	v_mfma_f32_16x16x32_bf16 v[52:55], v[108:111], v[104:107], v[52:55]
	v_mfma_f32_16x16x32_bf16 v[36:39], v[112:115], v[100:103], v[36:39]
	v_mfma_f32_16x16x32_bf16 v[56:59], v[112:115], v[104:107], v[56:59]
	v_mfma_f32_16x16x32_bf16 v[40:43], v[116:119], v[100:103], v[40:43]
	v_mfma_f32_16x16x32_bf16 v[60:63], v[116:119], v[104:107], v[60:63]
	v_mfma_f32_16x16x32_bf16 v[44:47], v[120:123], v[100:103], v[44:47]
	v_mfma_f32_16x16x32_bf16 v[64:67], v[120:123], v[104:107], v[64:67]
	v_mfma_f32_16x16x32_bf16 v[48:51], v[124:127], v[100:103], v[48:51]
	v_mfma_f32_16x16x32_bf16 v[68:71], v[124:127], v[104:107], v[68:71]
	global_load_dwordx4 v[100:103], v1, s[8:9] offset:1984
	global_load_dwordx4 v[104:107], v1, s[16:17] offset:1984
	global_load_dwordx4 v[108:111], v1, s[18:19] offset:1984
	global_load_dwordx4 v[112:115], v1, s[28:29] offset:1984
	global_load_dwordx4 v[116:119], v1, s[30:31] offset:1984
	global_load_dwordx4 v[120:123], v1, s[34:35] offset:1984
	global_load_dwordx4 v[124:127], v1, s[36:37] offset:1984
	s_waitcnt vmcnt(28)
	v_mfma_f32_16x16x32_bf16 v[32:35], v[136:139], v[128:131], v[32:35]
	v_mfma_f32_16x16x32_bf16 v[52:55], v[136:139], v[132:135], v[52:55]
	v_mfma_f32_16x16x32_bf16 v[36:39], v[140:143], v[128:131], v[36:39]
	v_mfma_f32_16x16x32_bf16 v[56:59], v[140:143], v[132:135], v[56:59]
	v_mfma_f32_16x16x32_bf16 v[40:43], v[144:147], v[128:131], v[40:43]
	v_mfma_f32_16x16x32_bf16 v[60:63], v[144:147], v[132:135], v[60:63]
	v_mfma_f32_16x16x32_bf16 v[44:47], v[148:151], v[128:131], v[44:47]
	v_mfma_f32_16x16x32_bf16 v[64:67], v[148:151], v[132:135], v[64:67]
	v_mfma_f32_16x16x32_bf16 v[48:51], v[152:155], v[128:131], v[48:51]
	v_mfma_f32_16x16x32_bf16 v[68:71], v[152:155], v[132:135], v[68:71]
	global_load_dwordx4 v[128:131], v1, s[8:9] offset:2048
	global_load_dwordx4 v[132:135], v1, s[16:17] offset:2048
	global_load_dwordx4 v[136:139], v1, s[18:19] offset:2048
	global_load_dwordx4 v[140:143], v1, s[28:29] offset:2048
	global_load_dwordx4 v[144:147], v1, s[30:31] offset:2048
	global_load_dwordx4 v[148:151], v1, s[34:35] offset:2048
	global_load_dwordx4 v[152:155], v1, s[36:37] offset:2048
	s_waitcnt vmcnt(28)
	v_mfma_f32_16x16x32_bf16 v[32:35], v[176:179], v[156:159], v[32:35]
	v_mfma_f32_16x16x32_bf16 v[52:55], v[176:179], v[172:175], v[52:55]
	v_mfma_f32_16x16x32_bf16 v[36:39], v[180:183], v[156:159], v[36:39]
	v_mfma_f32_16x16x32_bf16 v[56:59], v[180:183], v[172:175], v[56:59]
	v_mfma_f32_16x16x32_bf16 v[40:43], v[184:187], v[156:159], v[40:43]
	v_mfma_f32_16x16x32_bf16 v[60:63], v[184:187], v[172:175], v[60:63]
	v_mfma_f32_16x16x32_bf16 v[44:47], v[196:199], v[156:159], v[44:47]
	v_mfma_f32_16x16x32_bf16 v[64:67], v[196:199], v[172:175], v[64:67]
	v_mfma_f32_16x16x32_bf16 v[48:51], v[200:203], v[156:159], v[48:51]
	v_mfma_f32_16x16x32_bf16 v[68:71], v[200:203], v[172:175], v[68:71]
	global_load_dwordx4 v[156:159], v1, s[8:9] offset:2112
	global_load_dwordx4 v[172:175], v1, s[16:17] offset:2112
	global_load_dwordx4 v[176:179], v1, s[18:19] offset:2112
	global_load_dwordx4 v[180:183], v1, s[28:29] offset:2112
	global_load_dwordx4 v[184:187], v1, s[30:31] offset:2112
	global_load_dwordx4 v[196:199], v1, s[34:35] offset:2112
	global_load_dwordx4 v[200:203], v1, s[36:37] offset:2112
	s_waitcnt vmcnt(28)
	v_mfma_f32_16x16x32_bf16 v[32:35], v[212:215], v[204:207], v[32:35]
	v_mfma_f32_16x16x32_bf16 v[52:55], v[212:215], v[208:211], v[52:55]
	v_mfma_f32_16x16x32_bf16 v[36:39], v[234:237], v[204:207], v[36:39]
	v_mfma_f32_16x16x32_bf16 v[56:59], v[234:237], v[208:211], v[56:59]
	v_mfma_f32_16x16x32_bf16 v[40:43], v[238:241], v[204:207], v[40:43]
	v_mfma_f32_16x16x32_bf16 v[60:63], v[238:241], v[208:211], v[60:63]
	v_mfma_f32_16x16x32_bf16 v[44:47], v[242:245], v[204:207], v[44:47]
	v_mfma_f32_16x16x32_bf16 v[64:67], v[242:245], v[208:211], v[64:67]
	v_mfma_f32_16x16x32_bf16 v[48:51], v[246:249], v[204:207], v[48:51]
	v_mfma_f32_16x16x32_bf16 v[68:71], v[246:249], v[208:211], v[68:71]
	global_load_dwordx4 v[204:207], v1, s[8:9] offset:2176
	global_load_dwordx4 v[208:211], v1, s[16:17] offset:2176
	global_load_dwordx4 v[212:215], v1, s[18:19] offset:2176
	global_load_dwordx4 v[234:237], v1, s[28:29] offset:2176
	global_load_dwordx4 v[238:241], v1, s[30:31] offset:2176
	global_load_dwordx4 v[242:245], v1, s[34:35] offset:2176
	global_load_dwordx4 v[246:249], v1, s[36:37] offset:2176
	s_waitcnt vmcnt(28)
	v_mfma_f32_16x16x32_bf16 v[32:35], v[80:83], v[72:75], v[32:35]
	v_mfma_f32_16x16x32_bf16 v[52:55], v[80:83], v[76:79], v[52:55]
	v_mfma_f32_16x16x32_bf16 v[36:39], v[84:87], v[72:75], v[36:39]
	v_mfma_f32_16x16x32_bf16 v[56:59], v[84:87], v[76:79], v[56:59]
	v_mfma_f32_16x16x32_bf16 v[40:43], v[88:91], v[72:75], v[40:43]
	v_mfma_f32_16x16x32_bf16 v[60:63], v[88:91], v[76:79], v[60:63]
	v_mfma_f32_16x16x32_bf16 v[44:47], v[92:95], v[72:75], v[44:47]
	v_mfma_f32_16x16x32_bf16 v[64:67], v[92:95], v[76:79], v[64:67]
	v_mfma_f32_16x16x32_bf16 v[48:51], v[96:99], v[72:75], v[48:51]
	v_mfma_f32_16x16x32_bf16 v[68:71], v[96:99], v[76:79], v[68:71]
	global_load_dwordx4 v[72:75], v1, s[8:9] offset:2240
	global_load_dwordx4 v[76:79], v1, s[16:17] offset:2240
	global_load_dwordx4 v[80:83], v1, s[18:19] offset:2240
	global_load_dwordx4 v[84:87], v1, s[28:29] offset:2240
	global_load_dwordx4 v[88:91], v1, s[30:31] offset:2240
	global_load_dwordx4 v[92:95], v1, s[34:35] offset:2240
	global_load_dwordx4 v[96:99], v1, s[36:37] offset:2240
	s_waitcnt vmcnt(28)
	v_mfma_f32_16x16x32_bf16 v[32:35], v[108:111], v[100:103], v[32:35]
	v_mfma_f32_16x16x32_bf16 v[52:55], v[108:111], v[104:107], v[52:55]
	v_mfma_f32_16x16x32_bf16 v[36:39], v[112:115], v[100:103], v[36:39]
	v_mfma_f32_16x16x32_bf16 v[56:59], v[112:115], v[104:107], v[56:59]
	v_mfma_f32_16x16x32_bf16 v[40:43], v[116:119], v[100:103], v[40:43]
	v_mfma_f32_16x16x32_bf16 v[60:63], v[116:119], v[104:107], v[60:63]
	v_mfma_f32_16x16x32_bf16 v[44:47], v[120:123], v[100:103], v[44:47]
	v_mfma_f32_16x16x32_bf16 v[64:67], v[120:123], v[104:107], v[64:67]
	v_mfma_f32_16x16x32_bf16 v[48:51], v[124:127], v[100:103], v[48:51]
	v_mfma_f32_16x16x32_bf16 v[68:71], v[124:127], v[104:107], v[68:71]
	global_load_dwordx4 v[100:103], v1, s[8:9] offset:2304
	global_load_dwordx4 v[104:107], v1, s[16:17] offset:2304
	global_load_dwordx4 v[108:111], v1, s[18:19] offset:2304
	global_load_dwordx4 v[112:115], v1, s[28:29] offset:2304
	global_load_dwordx4 v[116:119], v1, s[30:31] offset:2304
	global_load_dwordx4 v[120:123], v1, s[34:35] offset:2304
	global_load_dwordx4 v[124:127], v1, s[36:37] offset:2304
	s_waitcnt vmcnt(28)
	v_mfma_f32_16x16x32_bf16 v[32:35], v[136:139], v[128:131], v[32:35]
	v_mfma_f32_16x16x32_bf16 v[52:55], v[136:139], v[132:135], v[52:55]
	v_mfma_f32_16x16x32_bf16 v[36:39], v[140:143], v[128:131], v[36:39]
	v_mfma_f32_16x16x32_bf16 v[56:59], v[140:143], v[132:135], v[56:59]
	v_mfma_f32_16x16x32_bf16 v[40:43], v[144:147], v[128:131], v[40:43]
	v_mfma_f32_16x16x32_bf16 v[60:63], v[144:147], v[132:135], v[60:63]
	v_mfma_f32_16x16x32_bf16 v[44:47], v[148:151], v[128:131], v[44:47]
	v_mfma_f32_16x16x32_bf16 v[64:67], v[148:151], v[132:135], v[64:67]
	v_mfma_f32_16x16x32_bf16 v[48:51], v[152:155], v[128:131], v[48:51]
	v_mfma_f32_16x16x32_bf16 v[68:71], v[152:155], v[132:135], v[68:71]
	global_load_dwordx4 v[128:131], v1, s[8:9] offset:2368
	global_load_dwordx4 v[132:135], v1, s[16:17] offset:2368
	global_load_dwordx4 v[136:139], v1, s[18:19] offset:2368
	global_load_dwordx4 v[140:143], v1, s[28:29] offset:2368
	global_load_dwordx4 v[144:147], v1, s[30:31] offset:2368
	global_load_dwordx4 v[148:151], v1, s[34:35] offset:2368
	global_load_dwordx4 v[152:155], v1, s[36:37] offset:2368
	s_waitcnt vmcnt(28)
	v_mfma_f32_16x16x32_bf16 v[32:35], v[176:179], v[156:159], v[32:35]
	v_mfma_f32_16x16x32_bf16 v[52:55], v[176:179], v[172:175], v[52:55]
	v_mfma_f32_16x16x32_bf16 v[36:39], v[180:183], v[156:159], v[36:39]
	v_mfma_f32_16x16x32_bf16 v[56:59], v[180:183], v[172:175], v[56:59]
	v_mfma_f32_16x16x32_bf16 v[40:43], v[184:187], v[156:159], v[40:43]
	v_mfma_f32_16x16x32_bf16 v[60:63], v[184:187], v[172:175], v[60:63]
	v_mfma_f32_16x16x32_bf16 v[44:47], v[196:199], v[156:159], v[44:47]
	v_mfma_f32_16x16x32_bf16 v[64:67], v[196:199], v[172:175], v[64:67]
	v_mfma_f32_16x16x32_bf16 v[48:51], v[200:203], v[156:159], v[48:51]
	v_mfma_f32_16x16x32_bf16 v[68:71], v[200:203], v[172:175], v[68:71]
	global_load_dwordx4 v[156:159], v1, s[8:9] offset:2432
	global_load_dwordx4 v[172:175], v1, s[16:17] offset:2432
	global_load_dwordx4 v[176:179], v1, s[18:19] offset:2432
	global_load_dwordx4 v[180:183], v1, s[28:29] offset:2432
	global_load_dwordx4 v[184:187], v1, s[30:31] offset:2432
	global_load_dwordx4 v[196:199], v1, s[34:35] offset:2432
	global_load_dwordx4 v[200:203], v1, s[36:37] offset:2432
	s_waitcnt vmcnt(28)
	v_mfma_f32_16x16x32_bf16 v[32:35], v[212:215], v[204:207], v[32:35]
	v_mfma_f32_16x16x32_bf16 v[52:55], v[212:215], v[208:211], v[52:55]
	v_mfma_f32_16x16x32_bf16 v[36:39], v[234:237], v[204:207], v[36:39]
	v_mfma_f32_16x16x32_bf16 v[56:59], v[234:237], v[208:211], v[56:59]
	v_mfma_f32_16x16x32_bf16 v[40:43], v[238:241], v[204:207], v[40:43]
	v_mfma_f32_16x16x32_bf16 v[60:63], v[238:241], v[208:211], v[60:63]
	v_mfma_f32_16x16x32_bf16 v[44:47], v[242:245], v[204:207], v[44:47]
	v_mfma_f32_16x16x32_bf16 v[64:67], v[242:245], v[208:211], v[64:67]
	v_mfma_f32_16x16x32_bf16 v[48:51], v[246:249], v[204:207], v[48:51]
	v_mfma_f32_16x16x32_bf16 v[68:71], v[246:249], v[208:211], v[68:71]
	global_load_dwordx4 v[204:207], v1, s[8:9] offset:2496
	global_load_dwordx4 v[208:211], v1, s[16:17] offset:2496
	global_load_dwordx4 v[212:215], v1, s[18:19] offset:2496
	global_load_dwordx4 v[234:237], v1, s[28:29] offset:2496
	global_load_dwordx4 v[238:241], v1, s[30:31] offset:2496
	global_load_dwordx4 v[242:245], v1, s[34:35] offset:2496
	global_load_dwordx4 v[246:249], v1, s[36:37] offset:2496
	s_waitcnt vmcnt(28)
	v_mfma_f32_16x16x32_bf16 v[32:35], v[80:83], v[72:75], v[32:35]
	v_mfma_f32_16x16x32_bf16 v[52:55], v[80:83], v[76:79], v[52:55]
	v_mfma_f32_16x16x32_bf16 v[36:39], v[84:87], v[72:75], v[36:39]
	v_mfma_f32_16x16x32_bf16 v[56:59], v[84:87], v[76:79], v[56:59]
	v_mfma_f32_16x16x32_bf16 v[40:43], v[88:91], v[72:75], v[40:43]
	v_mfma_f32_16x16x32_bf16 v[60:63], v[88:91], v[76:79], v[60:63]
	v_mfma_f32_16x16x32_bf16 v[44:47], v[92:95], v[72:75], v[44:47]
	v_mfma_f32_16x16x32_bf16 v[64:67], v[92:95], v[76:79], v[64:67]
	v_mfma_f32_16x16x32_bf16 v[48:51], v[96:99], v[72:75], v[48:51]
	v_mfma_f32_16x16x32_bf16 v[68:71], v[96:99], v[76:79], v[68:71]
	global_load_dwordx4 v[72:75], v1, s[8:9] offset:2560
	global_load_dwordx4 v[76:79], v1, s[16:17] offset:2560
	global_load_dwordx4 v[80:83], v1, s[18:19] offset:2560
	global_load_dwordx4 v[84:87], v1, s[28:29] offset:2560
	global_load_dwordx4 v[88:91], v1, s[30:31] offset:2560
	global_load_dwordx4 v[92:95], v1, s[34:35] offset:2560
	global_load_dwordx4 v[96:99], v1, s[36:37] offset:2560
	s_waitcnt vmcnt(28)
	v_mfma_f32_16x16x32_bf16 v[32:35], v[108:111], v[100:103], v[32:35]
	v_mfma_f32_16x16x32_bf16 v[52:55], v[108:111], v[104:107], v[52:55]
	v_mfma_f32_16x16x32_bf16 v[36:39], v[112:115], v[100:103], v[36:39]
	v_mfma_f32_16x16x32_bf16 v[56:59], v[112:115], v[104:107], v[56:59]
	v_mfma_f32_16x16x32_bf16 v[40:43], v[116:119], v[100:103], v[40:43]
	v_mfma_f32_16x16x32_bf16 v[60:63], v[116:119], v[104:107], v[60:63]
	v_mfma_f32_16x16x32_bf16 v[44:47], v[120:123], v[100:103], v[44:47]
	v_mfma_f32_16x16x32_bf16 v[64:67], v[120:123], v[104:107], v[64:67]
	v_mfma_f32_16x16x32_bf16 v[48:51], v[124:127], v[100:103], v[48:51]
	v_mfma_f32_16x16x32_bf16 v[68:71], v[124:127], v[104:107], v[68:71]
	global_load_dwordx4 v[100:103], v1, s[8:9] offset:2624
	global_load_dwordx4 v[104:107], v1, s[16:17] offset:2624
	global_load_dwordx4 v[108:111], v1, s[18:19] offset:2624
	global_load_dwordx4 v[112:115], v1, s[28:29] offset:2624
	global_load_dwordx4 v[116:119], v1, s[30:31] offset:2624
	global_load_dwordx4 v[120:123], v1, s[34:35] offset:2624
	global_load_dwordx4 v[124:127], v1, s[36:37] offset:2624
	s_waitcnt vmcnt(28)
	v_mfma_f32_16x16x32_bf16 v[32:35], v[136:139], v[128:131], v[32:35]
	v_mfma_f32_16x16x32_bf16 v[52:55], v[136:139], v[132:135], v[52:55]
	v_mfma_f32_16x16x32_bf16 v[36:39], v[140:143], v[128:131], v[36:39]
	v_mfma_f32_16x16x32_bf16 v[56:59], v[140:143], v[132:135], v[56:59]
	v_mfma_f32_16x16x32_bf16 v[40:43], v[144:147], v[128:131], v[40:43]
	v_mfma_f32_16x16x32_bf16 v[60:63], v[144:147], v[132:135], v[60:63]
	v_mfma_f32_16x16x32_bf16 v[44:47], v[148:151], v[128:131], v[44:47]
	v_mfma_f32_16x16x32_bf16 v[64:67], v[148:151], v[132:135], v[64:67]
	v_mfma_f32_16x16x32_bf16 v[48:51], v[152:155], v[128:131], v[48:51]
	v_mfma_f32_16x16x32_bf16 v[68:71], v[152:155], v[132:135], v[68:71]
	global_load_dwordx4 v[128:131], v1, s[8:9] offset:2688
	global_load_dwordx4 v[132:135], v1, s[16:17] offset:2688
	global_load_dwordx4 v[136:139], v1, s[18:19] offset:2688
	global_load_dwordx4 v[140:143], v1, s[28:29] offset:2688
	global_load_dwordx4 v[144:147], v1, s[30:31] offset:2688
	global_load_dwordx4 v[148:151], v1, s[34:35] offset:2688
	global_load_dwordx4 v[152:155], v1, s[36:37] offset:2688
	s_waitcnt vmcnt(28)
	v_mfma_f32_16x16x32_bf16 v[32:35], v[176:179], v[156:159], v[32:35]
	v_mfma_f32_16x16x32_bf16 v[52:55], v[176:179], v[172:175], v[52:55]
	v_mfma_f32_16x16x32_bf16 v[36:39], v[180:183], v[156:159], v[36:39]
	v_mfma_f32_16x16x32_bf16 v[56:59], v[180:183], v[172:175], v[56:59]
	v_mfma_f32_16x16x32_bf16 v[40:43], v[184:187], v[156:159], v[40:43]
	v_mfma_f32_16x16x32_bf16 v[60:63], v[184:187], v[172:175], v[60:63]
	v_mfma_f32_16x16x32_bf16 v[44:47], v[196:199], v[156:159], v[44:47]
	v_mfma_f32_16x16x32_bf16 v[64:67], v[196:199], v[172:175], v[64:67]
	v_mfma_f32_16x16x32_bf16 v[48:51], v[200:203], v[156:159], v[48:51]
	v_mfma_f32_16x16x32_bf16 v[68:71], v[200:203], v[172:175], v[68:71]
	global_load_dwordx4 v[156:159], v1, s[8:9] offset:2752
	global_load_dwordx4 v[172:175], v1, s[16:17] offset:2752
	global_load_dwordx4 v[176:179], v1, s[18:19] offset:2752
	global_load_dwordx4 v[180:183], v1, s[28:29] offset:2752
	global_load_dwordx4 v[184:187], v1, s[30:31] offset:2752
	global_load_dwordx4 v[196:199], v1, s[34:35] offset:2752
	global_load_dwordx4 v[200:203], v1, s[36:37] offset:2752
	s_waitcnt vmcnt(28)
	v_mfma_f32_16x16x32_bf16 v[32:35], v[212:215], v[204:207], v[32:35]
	v_mfma_f32_16x16x32_bf16 v[52:55], v[212:215], v[208:211], v[52:55]
	v_mfma_f32_16x16x32_bf16 v[36:39], v[234:237], v[204:207], v[36:39]
	v_mfma_f32_16x16x32_bf16 v[56:59], v[234:237], v[208:211], v[56:59]
	v_mfma_f32_16x16x32_bf16 v[40:43], v[238:241], v[204:207], v[40:43]
	v_mfma_f32_16x16x32_bf16 v[60:63], v[238:241], v[208:211], v[60:63]
	v_mfma_f32_16x16x32_bf16 v[44:47], v[242:245], v[204:207], v[44:47]
	v_mfma_f32_16x16x32_bf16 v[64:67], v[242:245], v[208:211], v[64:67]
	v_mfma_f32_16x16x32_bf16 v[48:51], v[246:249], v[204:207], v[48:51]
	v_mfma_f32_16x16x32_bf16 v[68:71], v[246:249], v[208:211], v[68:71]
	global_load_dwordx4 v[204:207], v1, s[8:9] offset:2816
	global_load_dwordx4 v[208:211], v1, s[16:17] offset:2816
	global_load_dwordx4 v[212:215], v1, s[18:19] offset:2816
	global_load_dwordx4 v[234:237], v1, s[28:29] offset:2816
	global_load_dwordx4 v[238:241], v1, s[30:31] offset:2816
	global_load_dwordx4 v[242:245], v1, s[34:35] offset:2816
	global_load_dwordx4 v[246:249], v1, s[36:37] offset:2816
	s_waitcnt vmcnt(28)
	v_mfma_f32_16x16x32_bf16 v[32:35], v[80:83], v[72:75], v[32:35]
	v_mfma_f32_16x16x32_bf16 v[52:55], v[80:83], v[76:79], v[52:55]
	v_mfma_f32_16x16x32_bf16 v[36:39], v[84:87], v[72:75], v[36:39]
	v_mfma_f32_16x16x32_bf16 v[56:59], v[84:87], v[76:79], v[56:59]
	v_mfma_f32_16x16x32_bf16 v[40:43], v[88:91], v[72:75], v[40:43]
	v_mfma_f32_16x16x32_bf16 v[60:63], v[88:91], v[76:79], v[60:63]
	v_mfma_f32_16x16x32_bf16 v[44:47], v[92:95], v[72:75], v[44:47]
	v_mfma_f32_16x16x32_bf16 v[64:67], v[92:95], v[76:79], v[64:67]
	v_mfma_f32_16x16x32_bf16 v[48:51], v[96:99], v[72:75], v[48:51]
	v_mfma_f32_16x16x32_bf16 v[68:71], v[96:99], v[76:79], v[68:71]
	global_load_dwordx4 v[72:75], v1, s[8:9] offset:2880
	global_load_dwordx4 v[76:79], v1, s[16:17] offset:2880
	global_load_dwordx4 v[80:83], v1, s[18:19] offset:2880
	global_load_dwordx4 v[84:87], v1, s[28:29] offset:2880
	global_load_dwordx4 v[88:91], v1, s[30:31] offset:2880
	global_load_dwordx4 v[92:95], v1, s[34:35] offset:2880
	global_load_dwordx4 v[96:99], v1, s[36:37] offset:2880
	s_waitcnt vmcnt(28)
	v_mfma_f32_16x16x32_bf16 v[32:35], v[108:111], v[100:103], v[32:35]
	v_mfma_f32_16x16x32_bf16 v[52:55], v[108:111], v[104:107], v[52:55]
	v_mfma_f32_16x16x32_bf16 v[36:39], v[112:115], v[100:103], v[36:39]
	v_mfma_f32_16x16x32_bf16 v[56:59], v[112:115], v[104:107], v[56:59]
	v_mfma_f32_16x16x32_bf16 v[40:43], v[116:119], v[100:103], v[40:43]
	v_mfma_f32_16x16x32_bf16 v[60:63], v[116:119], v[104:107], v[60:63]
	v_mfma_f32_16x16x32_bf16 v[44:47], v[120:123], v[100:103], v[44:47]
	v_mfma_f32_16x16x32_bf16 v[64:67], v[120:123], v[104:107], v[64:67]
	v_mfma_f32_16x16x32_bf16 v[48:51], v[124:127], v[100:103], v[48:51]
	v_mfma_f32_16x16x32_bf16 v[68:71], v[124:127], v[104:107], v[68:71]
	global_load_dwordx4 v[100:103], v1, s[8:9] offset:2944
	global_load_dwordx4 v[104:107], v1, s[16:17] offset:2944
	global_load_dwordx4 v[108:111], v1, s[18:19] offset:2944
	global_load_dwordx4 v[112:115], v1, s[28:29] offset:2944
	global_load_dwordx4 v[116:119], v1, s[30:31] offset:2944
	global_load_dwordx4 v[120:123], v1, s[34:35] offset:2944
	global_load_dwordx4 v[124:127], v1, s[36:37] offset:2944
	s_waitcnt vmcnt(28)
	v_mfma_f32_16x16x32_bf16 v[32:35], v[136:139], v[128:131], v[32:35]
	v_mfma_f32_16x16x32_bf16 v[52:55], v[136:139], v[132:135], v[52:55]
	v_mfma_f32_16x16x32_bf16 v[36:39], v[140:143], v[128:131], v[36:39]
	v_mfma_f32_16x16x32_bf16 v[56:59], v[140:143], v[132:135], v[56:59]
	v_mfma_f32_16x16x32_bf16 v[40:43], v[144:147], v[128:131], v[40:43]
	v_mfma_f32_16x16x32_bf16 v[60:63], v[144:147], v[132:135], v[60:63]
	v_mfma_f32_16x16x32_bf16 v[44:47], v[148:151], v[128:131], v[44:47]
	v_mfma_f32_16x16x32_bf16 v[64:67], v[148:151], v[132:135], v[64:67]
	v_mfma_f32_16x16x32_bf16 v[48:51], v[152:155], v[128:131], v[48:51]
	v_mfma_f32_16x16x32_bf16 v[68:71], v[152:155], v[132:135], v[68:71]
	global_load_dwordx4 v[128:131], v1, s[8:9] offset:3008
	global_load_dwordx4 v[132:135], v1, s[16:17] offset:3008
	global_load_dwordx4 v[136:139], v1, s[18:19] offset:3008
	global_load_dwordx4 v[140:143], v1, s[28:29] offset:3008
	global_load_dwordx4 v[144:147], v1, s[30:31] offset:3008
	global_load_dwordx4 v[148:151], v1, s[34:35] offset:3008
	global_load_dwordx4 v[152:155], v1, s[36:37] offset:3008
	s_waitcnt vmcnt(28)
	v_mfma_f32_16x16x32_bf16 v[32:35], v[176:179], v[156:159], v[32:35]
	v_mfma_f32_16x16x32_bf16 v[52:55], v[176:179], v[172:175], v[52:55]
	v_mfma_f32_16x16x32_bf16 v[36:39], v[180:183], v[156:159], v[36:39]
	v_mfma_f32_16x16x32_bf16 v[56:59], v[180:183], v[172:175], v[56:59]
	v_mfma_f32_16x16x32_bf16 v[40:43], v[184:187], v[156:159], v[40:43]
	v_mfma_f32_16x16x32_bf16 v[60:63], v[184:187], v[172:175], v[60:63]
	v_mfma_f32_16x16x32_bf16 v[44:47], v[196:199], v[156:159], v[44:47]
	v_mfma_f32_16x16x32_bf16 v[64:67], v[196:199], v[172:175], v[64:67]
	v_mfma_f32_16x16x32_bf16 v[48:51], v[200:203], v[156:159], v[48:51]
	v_mfma_f32_16x16x32_bf16 v[68:71], v[200:203], v[172:175], v[68:71]
	global_load_dwordx4 v[156:159], v1, s[8:9] offset:3072
	global_load_dwordx4 v[172:175], v1, s[16:17] offset:3072
	global_load_dwordx4 v[176:179], v1, s[18:19] offset:3072
	global_load_dwordx4 v[180:183], v1, s[28:29] offset:3072
	global_load_dwordx4 v[184:187], v1, s[30:31] offset:3072
	global_load_dwordx4 v[196:199], v1, s[34:35] offset:3072
	global_load_dwordx4 v[200:203], v1, s[36:37] offset:3072
	s_waitcnt vmcnt(28)
	v_mfma_f32_16x16x32_bf16 v[32:35], v[212:215], v[204:207], v[32:35]
	v_mfma_f32_16x16x32_bf16 v[52:55], v[212:215], v[208:211], v[52:55]
	v_mfma_f32_16x16x32_bf16 v[36:39], v[234:237], v[204:207], v[36:39]
	v_mfma_f32_16x16x32_bf16 v[56:59], v[234:237], v[208:211], v[56:59]
	v_mfma_f32_16x16x32_bf16 v[40:43], v[238:241], v[204:207], v[40:43]
	v_mfma_f32_16x16x32_bf16 v[60:63], v[238:241], v[208:211], v[60:63]
	v_mfma_f32_16x16x32_bf16 v[44:47], v[242:245], v[204:207], v[44:47]
	v_mfma_f32_16x16x32_bf16 v[64:67], v[242:245], v[208:211], v[64:67]
	v_mfma_f32_16x16x32_bf16 v[48:51], v[246:249], v[204:207], v[48:51]
	v_mfma_f32_16x16x32_bf16 v[68:71], v[246:249], v[208:211], v[68:71]
	global_load_dwordx4 v[204:207], v1, s[8:9] offset:3136
	global_load_dwordx4 v[208:211], v1, s[16:17] offset:3136
	global_load_dwordx4 v[212:215], v1, s[18:19] offset:3136
	global_load_dwordx4 v[234:237], v1, s[28:29] offset:3136
	global_load_dwordx4 v[238:241], v1, s[30:31] offset:3136
	global_load_dwordx4 v[242:245], v1, s[34:35] offset:3136
	global_load_dwordx4 v[246:249], v1, s[36:37] offset:3136
	s_waitcnt vmcnt(28)
	v_mfma_f32_16x16x32_bf16 v[32:35], v[80:83], v[72:75], v[32:35]
	v_mfma_f32_16x16x32_bf16 v[52:55], v[80:83], v[76:79], v[52:55]
	v_mfma_f32_16x16x32_bf16 v[36:39], v[84:87], v[72:75], v[36:39]
	v_mfma_f32_16x16x32_bf16 v[56:59], v[84:87], v[76:79], v[56:59]
	v_mfma_f32_16x16x32_bf16 v[40:43], v[88:91], v[72:75], v[40:43]
	v_mfma_f32_16x16x32_bf16 v[60:63], v[88:91], v[76:79], v[60:63]
	v_mfma_f32_16x16x32_bf16 v[44:47], v[92:95], v[72:75], v[44:47]
	v_mfma_f32_16x16x32_bf16 v[64:67], v[92:95], v[76:79], v[64:67]
	v_mfma_f32_16x16x32_bf16 v[48:51], v[96:99], v[72:75], v[48:51]
	v_mfma_f32_16x16x32_bf16 v[68:71], v[96:99], v[76:79], v[68:71]
	global_load_dwordx4 v[72:75], v1, s[8:9] offset:3200
	global_load_dwordx4 v[76:79], v1, s[16:17] offset:3200
	global_load_dwordx4 v[80:83], v1, s[18:19] offset:3200
	global_load_dwordx4 v[84:87], v1, s[28:29] offset:3200
	global_load_dwordx4 v[88:91], v1, s[30:31] offset:3200
	global_load_dwordx4 v[92:95], v1, s[34:35] offset:3200
	global_load_dwordx4 v[96:99], v1, s[36:37] offset:3200
	s_waitcnt vmcnt(28)
	v_mfma_f32_16x16x32_bf16 v[32:35], v[108:111], v[100:103], v[32:35]
	v_mfma_f32_16x16x32_bf16 v[52:55], v[108:111], v[104:107], v[52:55]
	v_mfma_f32_16x16x32_bf16 v[36:39], v[112:115], v[100:103], v[36:39]
	v_mfma_f32_16x16x32_bf16 v[56:59], v[112:115], v[104:107], v[56:59]
	v_mfma_f32_16x16x32_bf16 v[40:43], v[116:119], v[100:103], v[40:43]
	v_mfma_f32_16x16x32_bf16 v[60:63], v[116:119], v[104:107], v[60:63]
	v_mfma_f32_16x16x32_bf16 v[44:47], v[120:123], v[100:103], v[44:47]
	v_mfma_f32_16x16x32_bf16 v[64:67], v[120:123], v[104:107], v[64:67]
	v_mfma_f32_16x16x32_bf16 v[48:51], v[124:127], v[100:103], v[48:51]
	v_mfma_f32_16x16x32_bf16 v[68:71], v[124:127], v[104:107], v[68:71]
	global_load_dwordx4 v[100:103], v1, s[8:9] offset:3264
	global_load_dwordx4 v[104:107], v1, s[16:17] offset:3264
	global_load_dwordx4 v[108:111], v1, s[18:19] offset:3264
	global_load_dwordx4 v[112:115], v1, s[28:29] offset:3264
	global_load_dwordx4 v[116:119], v1, s[30:31] offset:3264
	global_load_dwordx4 v[120:123], v1, s[34:35] offset:3264
	global_load_dwordx4 v[124:127], v1, s[36:37] offset:3264
	s_waitcnt vmcnt(28)
	v_mfma_f32_16x16x32_bf16 v[32:35], v[136:139], v[128:131], v[32:35]
	v_mfma_f32_16x16x32_bf16 v[52:55], v[136:139], v[132:135], v[52:55]
	v_mfma_f32_16x16x32_bf16 v[36:39], v[140:143], v[128:131], v[36:39]
	v_mfma_f32_16x16x32_bf16 v[56:59], v[140:143], v[132:135], v[56:59]
	v_mfma_f32_16x16x32_bf16 v[40:43], v[144:147], v[128:131], v[40:43]
	v_mfma_f32_16x16x32_bf16 v[60:63], v[144:147], v[132:135], v[60:63]
	v_mfma_f32_16x16x32_bf16 v[44:47], v[148:151], v[128:131], v[44:47]
	v_mfma_f32_16x16x32_bf16 v[64:67], v[148:151], v[132:135], v[64:67]
	v_mfma_f32_16x16x32_bf16 v[48:51], v[152:155], v[128:131], v[48:51]
	v_mfma_f32_16x16x32_bf16 v[68:71], v[152:155], v[132:135], v[68:71]
	global_load_dwordx4 v[128:131], v1, s[8:9] offset:3328
	global_load_dwordx4 v[132:135], v1, s[16:17] offset:3328
	global_load_dwordx4 v[136:139], v1, s[18:19] offset:3328
	global_load_dwordx4 v[140:143], v1, s[28:29] offset:3328
	global_load_dwordx4 v[144:147], v1, s[30:31] offset:3328
	global_load_dwordx4 v[148:151], v1, s[34:35] offset:3328
	global_load_dwordx4 v[152:155], v1, s[36:37] offset:3328
	s_waitcnt vmcnt(28)
	v_mfma_f32_16x16x32_bf16 v[32:35], v[176:179], v[156:159], v[32:35]
	v_mfma_f32_16x16x32_bf16 v[52:55], v[176:179], v[172:175], v[52:55]
	v_mfma_f32_16x16x32_bf16 v[36:39], v[180:183], v[156:159], v[36:39]
	v_mfma_f32_16x16x32_bf16 v[56:59], v[180:183], v[172:175], v[56:59]
	v_mfma_f32_16x16x32_bf16 v[40:43], v[184:187], v[156:159], v[40:43]
	v_mfma_f32_16x16x32_bf16 v[60:63], v[184:187], v[172:175], v[60:63]
	v_mfma_f32_16x16x32_bf16 v[44:47], v[196:199], v[156:159], v[44:47]
	v_mfma_f32_16x16x32_bf16 v[64:67], v[196:199], v[172:175], v[64:67]
	v_mfma_f32_16x16x32_bf16 v[48:51], v[200:203], v[156:159], v[48:51]
	v_mfma_f32_16x16x32_bf16 v[68:71], v[200:203], v[172:175], v[68:71]
	global_load_dwordx4 v[156:159], v1, s[8:9] offset:3392
	global_load_dwordx4 v[172:175], v1, s[16:17] offset:3392
	global_load_dwordx4 v[176:179], v1, s[18:19] offset:3392
	global_load_dwordx4 v[180:183], v1, s[28:29] offset:3392
	global_load_dwordx4 v[184:187], v1, s[30:31] offset:3392
	global_load_dwordx4 v[196:199], v1, s[34:35] offset:3392
	global_load_dwordx4 v[200:203], v1, s[36:37] offset:3392
	s_waitcnt vmcnt(28)
	v_mfma_f32_16x16x32_bf16 v[32:35], v[212:215], v[204:207], v[32:35]
	v_mfma_f32_16x16x32_bf16 v[52:55], v[212:215], v[208:211], v[52:55]
	v_mfma_f32_16x16x32_bf16 v[36:39], v[234:237], v[204:207], v[36:39]
	v_mfma_f32_16x16x32_bf16 v[56:59], v[234:237], v[208:211], v[56:59]
	v_mfma_f32_16x16x32_bf16 v[40:43], v[238:241], v[204:207], v[40:43]
	v_mfma_f32_16x16x32_bf16 v[60:63], v[238:241], v[208:211], v[60:63]
	v_mfma_f32_16x16x32_bf16 v[44:47], v[242:245], v[204:207], v[44:47]
	v_mfma_f32_16x16x32_bf16 v[64:67], v[242:245], v[208:211], v[64:67]
	v_mfma_f32_16x16x32_bf16 v[48:51], v[246:249], v[204:207], v[48:51]
	v_mfma_f32_16x16x32_bf16 v[68:71], v[246:249], v[208:211], v[68:71]
	global_load_dwordx4 v[204:207], v1, s[8:9] offset:3456
	global_load_dwordx4 v[208:211], v1, s[16:17] offset:3456
	global_load_dwordx4 v[212:215], v1, s[18:19] offset:3456
	global_load_dwordx4 v[234:237], v1, s[28:29] offset:3456
	global_load_dwordx4 v[238:241], v1, s[30:31] offset:3456
	global_load_dwordx4 v[242:245], v1, s[34:35] offset:3456
	global_load_dwordx4 v[246:249], v1, s[36:37] offset:3456
	s_waitcnt vmcnt(28)
	v_mfma_f32_16x16x32_bf16 v[32:35], v[80:83], v[72:75], v[32:35]
	v_mfma_f32_16x16x32_bf16 v[52:55], v[80:83], v[76:79], v[52:55]
	v_mfma_f32_16x16x32_bf16 v[36:39], v[84:87], v[72:75], v[36:39]
	v_mfma_f32_16x16x32_bf16 v[56:59], v[84:87], v[76:79], v[56:59]
	v_mfma_f32_16x16x32_bf16 v[40:43], v[88:91], v[72:75], v[40:43]
	v_mfma_f32_16x16x32_bf16 v[60:63], v[88:91], v[76:79], v[60:63]
	v_mfma_f32_16x16x32_bf16 v[44:47], v[92:95], v[72:75], v[44:47]
	v_mfma_f32_16x16x32_bf16 v[64:67], v[92:95], v[76:79], v[64:67]
	v_mfma_f32_16x16x32_bf16 v[48:51], v[96:99], v[72:75], v[48:51]
	v_mfma_f32_16x16x32_bf16 v[68:71], v[96:99], v[76:79], v[68:71]
	global_load_dwordx4 v[72:75], v1, s[8:9] offset:3520
	global_load_dwordx4 v[76:79], v1, s[16:17] offset:3520
	global_load_dwordx4 v[80:83], v1, s[18:19] offset:3520
	global_load_dwordx4 v[84:87], v1, s[28:29] offset:3520
	global_load_dwordx4 v[88:91], v1, s[30:31] offset:3520
	global_load_dwordx4 v[92:95], v1, s[34:35] offset:3520
	global_load_dwordx4 v[96:99], v1, s[36:37] offset:3520
	s_waitcnt vmcnt(28)
	v_mfma_f32_16x16x32_bf16 v[32:35], v[108:111], v[100:103], v[32:35]
	v_mfma_f32_16x16x32_bf16 v[52:55], v[108:111], v[104:107], v[52:55]
	v_mfma_f32_16x16x32_bf16 v[36:39], v[112:115], v[100:103], v[36:39]
	v_mfma_f32_16x16x32_bf16 v[56:59], v[112:115], v[104:107], v[56:59]
	v_mfma_f32_16x16x32_bf16 v[40:43], v[116:119], v[100:103], v[40:43]
	v_mfma_f32_16x16x32_bf16 v[60:63], v[116:119], v[104:107], v[60:63]
	v_mfma_f32_16x16x32_bf16 v[44:47], v[120:123], v[100:103], v[44:47]
	v_mfma_f32_16x16x32_bf16 v[64:67], v[120:123], v[104:107], v[64:67]
	v_mfma_f32_16x16x32_bf16 v[48:51], v[124:127], v[100:103], v[48:51]
	v_mfma_f32_16x16x32_bf16 v[68:71], v[124:127], v[104:107], v[68:71]
	global_load_dwordx4 v[100:103], v1, s[8:9] offset:3584
	global_load_dwordx4 v[104:107], v1, s[16:17] offset:3584
	global_load_dwordx4 v[108:111], v1, s[18:19] offset:3584
	global_load_dwordx4 v[112:115], v1, s[28:29] offset:3584
	global_load_dwordx4 v[116:119], v1, s[30:31] offset:3584
	global_load_dwordx4 v[120:123], v1, s[34:35] offset:3584
	global_load_dwordx4 v[124:127], v1, s[36:37] offset:3584
	s_waitcnt vmcnt(28)
	v_mfma_f32_16x16x32_bf16 v[32:35], v[136:139], v[128:131], v[32:35]
	v_mfma_f32_16x16x32_bf16 v[52:55], v[136:139], v[132:135], v[52:55]
	v_mfma_f32_16x16x32_bf16 v[36:39], v[140:143], v[128:131], v[36:39]
	v_mfma_f32_16x16x32_bf16 v[56:59], v[140:143], v[132:135], v[56:59]
	v_mfma_f32_16x16x32_bf16 v[40:43], v[144:147], v[128:131], v[40:43]
	v_mfma_f32_16x16x32_bf16 v[60:63], v[144:147], v[132:135], v[60:63]
	v_mfma_f32_16x16x32_bf16 v[44:47], v[148:151], v[128:131], v[44:47]
	v_mfma_f32_16x16x32_bf16 v[64:67], v[148:151], v[132:135], v[64:67]
	v_mfma_f32_16x16x32_bf16 v[48:51], v[152:155], v[128:131], v[48:51]
	v_mfma_f32_16x16x32_bf16 v[68:71], v[152:155], v[132:135], v[68:71]
	global_load_dwordx4 v[128:131], v1, s[8:9] offset:3648
	global_load_dwordx4 v[132:135], v1, s[16:17] offset:3648
	global_load_dwordx4 v[136:139], v1, s[18:19] offset:3648
	global_load_dwordx4 v[140:143], v1, s[28:29] offset:3648
	global_load_dwordx4 v[144:147], v1, s[30:31] offset:3648
	global_load_dwordx4 v[148:151], v1, s[34:35] offset:3648
	global_load_dwordx4 v[152:155], v1, s[36:37] offset:3648
	s_waitcnt vmcnt(28)
	v_mfma_f32_16x16x32_bf16 v[32:35], v[176:179], v[156:159], v[32:35]
	v_mfma_f32_16x16x32_bf16 v[52:55], v[176:179], v[172:175], v[52:55]
	v_mfma_f32_16x16x32_bf16 v[36:39], v[180:183], v[156:159], v[36:39]
	v_mfma_f32_16x16x32_bf16 v[56:59], v[180:183], v[172:175], v[56:59]
	v_mfma_f32_16x16x32_bf16 v[40:43], v[184:187], v[156:159], v[40:43]
	v_mfma_f32_16x16x32_bf16 v[60:63], v[184:187], v[172:175], v[60:63]
	v_mfma_f32_16x16x32_bf16 v[44:47], v[196:199], v[156:159], v[44:47]
	v_mfma_f32_16x16x32_bf16 v[64:67], v[196:199], v[172:175], v[64:67]
	v_mfma_f32_16x16x32_bf16 v[48:51], v[200:203], v[156:159], v[48:51]
	v_mfma_f32_16x16x32_bf16 v[68:71], v[200:203], v[172:175], v[68:71]
	global_load_dwordx4 v[156:159], v1, s[8:9] offset:3712
	global_load_dwordx4 v[172:175], v1, s[16:17] offset:3712
	global_load_dwordx4 v[176:179], v1, s[18:19] offset:3712
	global_load_dwordx4 v[180:183], v1, s[28:29] offset:3712
	global_load_dwordx4 v[184:187], v1, s[30:31] offset:3712
	global_load_dwordx4 v[196:199], v1, s[34:35] offset:3712
	global_load_dwordx4 v[200:203], v1, s[36:37] offset:3712
	s_waitcnt vmcnt(28)
	v_mfma_f32_16x16x32_bf16 v[32:35], v[212:215], v[204:207], v[32:35]
	v_mfma_f32_16x16x32_bf16 v[52:55], v[212:215], v[208:211], v[52:55]
	v_mfma_f32_16x16x32_bf16 v[36:39], v[234:237], v[204:207], v[36:39]
	v_mfma_f32_16x16x32_bf16 v[56:59], v[234:237], v[208:211], v[56:59]
	v_mfma_f32_16x16x32_bf16 v[40:43], v[238:241], v[204:207], v[40:43]
	v_mfma_f32_16x16x32_bf16 v[60:63], v[238:241], v[208:211], v[60:63]
	v_mfma_f32_16x16x32_bf16 v[44:47], v[242:245], v[204:207], v[44:47]
	v_mfma_f32_16x16x32_bf16 v[64:67], v[242:245], v[208:211], v[64:67]
	v_mfma_f32_16x16x32_bf16 v[48:51], v[246:249], v[204:207], v[48:51]
	v_mfma_f32_16x16x32_bf16 v[68:71], v[246:249], v[208:211], v[68:71]
	global_load_dwordx4 v[204:207], v1, s[8:9] offset:3776
	global_load_dwordx4 v[208:211], v1, s[16:17] offset:3776
	global_load_dwordx4 v[212:215], v1, s[18:19] offset:3776
	global_load_dwordx4 v[234:237], v1, s[28:29] offset:3776
	global_load_dwordx4 v[238:241], v1, s[30:31] offset:3776
	global_load_dwordx4 v[242:245], v1, s[34:35] offset:3776
	global_load_dwordx4 v[246:249], v1, s[36:37] offset:3776
	s_waitcnt vmcnt(28)
	v_mfma_f32_16x16x32_bf16 v[32:35], v[80:83], v[72:75], v[32:35]
	v_mfma_f32_16x16x32_bf16 v[52:55], v[80:83], v[76:79], v[52:55]
	v_mfma_f32_16x16x32_bf16 v[36:39], v[84:87], v[72:75], v[36:39]
	v_mfma_f32_16x16x32_bf16 v[56:59], v[84:87], v[76:79], v[56:59]
	v_mfma_f32_16x16x32_bf16 v[40:43], v[88:91], v[72:75], v[40:43]
	v_mfma_f32_16x16x32_bf16 v[60:63], v[88:91], v[76:79], v[60:63]
	v_mfma_f32_16x16x32_bf16 v[44:47], v[92:95], v[72:75], v[44:47]
	v_mfma_f32_16x16x32_bf16 v[64:67], v[92:95], v[76:79], v[64:67]
	v_mfma_f32_16x16x32_bf16 v[48:51], v[96:99], v[72:75], v[48:51]
	v_mfma_f32_16x16x32_bf16 v[68:71], v[96:99], v[76:79], v[68:71]
	global_load_dwordx4 v[72:75], v1, s[8:9] offset:3840
	global_load_dwordx4 v[76:79], v1, s[16:17] offset:3840
	global_load_dwordx4 v[80:83], v1, s[18:19] offset:3840
	global_load_dwordx4 v[84:87], v1, s[28:29] offset:3840
	global_load_dwordx4 v[88:91], v1, s[30:31] offset:3840
	global_load_dwordx4 v[92:95], v1, s[34:35] offset:3840
	global_load_dwordx4 v[96:99], v1, s[36:37] offset:3840
	s_waitcnt vmcnt(28)
	v_mfma_f32_16x16x32_bf16 v[32:35], v[108:111], v[100:103], v[32:35]
	v_mfma_f32_16x16x32_bf16 v[52:55], v[108:111], v[104:107], v[52:55]
	v_mfma_f32_16x16x32_bf16 v[36:39], v[112:115], v[100:103], v[36:39]
	v_mfma_f32_16x16x32_bf16 v[56:59], v[112:115], v[104:107], v[56:59]
	v_mfma_f32_16x16x32_bf16 v[40:43], v[116:119], v[100:103], v[40:43]
	v_mfma_f32_16x16x32_bf16 v[60:63], v[116:119], v[104:107], v[60:63]
	v_mfma_f32_16x16x32_bf16 v[44:47], v[120:123], v[100:103], v[44:47]
	v_mfma_f32_16x16x32_bf16 v[64:67], v[120:123], v[104:107], v[64:67]
	v_mfma_f32_16x16x32_bf16 v[48:51], v[124:127], v[100:103], v[48:51]
	v_mfma_f32_16x16x32_bf16 v[68:71], v[124:127], v[104:107], v[68:71]
	global_load_dwordx4 v[100:103], v1, s[8:9] offset:3904
	global_load_dwordx4 v[104:107], v1, s[16:17] offset:3904
	global_load_dwordx4 v[108:111], v1, s[18:19] offset:3904
	global_load_dwordx4 v[112:115], v1, s[28:29] offset:3904
	global_load_dwordx4 v[116:119], v1, s[30:31] offset:3904
	global_load_dwordx4 v[120:123], v1, s[34:35] offset:3904
	global_load_dwordx4 v[124:127], v1, s[36:37] offset:3904
	s_waitcnt vmcnt(28)
	v_mfma_f32_16x16x32_bf16 v[32:35], v[136:139], v[128:131], v[32:35]
	v_mfma_f32_16x16x32_bf16 v[52:55], v[136:139], v[132:135], v[52:55]
	v_mfma_f32_16x16x32_bf16 v[36:39], v[140:143], v[128:131], v[36:39]
	v_mfma_f32_16x16x32_bf16 v[56:59], v[140:143], v[132:135], v[56:59]
	v_mfma_f32_16x16x32_bf16 v[40:43], v[144:147], v[128:131], v[40:43]
	v_mfma_f32_16x16x32_bf16 v[60:63], v[144:147], v[132:135], v[60:63]
	v_mfma_f32_16x16x32_bf16 v[44:47], v[148:151], v[128:131], v[44:47]
	v_mfma_f32_16x16x32_bf16 v[64:67], v[148:151], v[132:135], v[64:67]
	v_mfma_f32_16x16x32_bf16 v[48:51], v[152:155], v[128:131], v[48:51]
	v_mfma_f32_16x16x32_bf16 v[68:71], v[152:155], v[132:135], v[68:71]
	global_load_dwordx4 v[128:131], v1, s[8:9] offset:3968
	global_load_dwordx4 v[132:135], v1, s[16:17] offset:3968
	global_load_dwordx4 v[136:139], v1, s[18:19] offset:3968
	global_load_dwordx4 v[140:143], v1, s[28:29] offset:3968
	global_load_dwordx4 v[144:147], v1, s[30:31] offset:3968
	global_load_dwordx4 v[148:151], v1, s[34:35] offset:3968
	global_load_dwordx4 v[152:155], v1, s[36:37] offset:3968
	s_waitcnt vmcnt(28)
	v_mfma_f32_16x16x32_bf16 v[32:35], v[176:179], v[156:159], v[32:35]
	v_mfma_f32_16x16x32_bf16 v[52:55], v[176:179], v[172:175], v[52:55]
	v_mfma_f32_16x16x32_bf16 v[36:39], v[180:183], v[156:159], v[36:39]
	v_mfma_f32_16x16x32_bf16 v[56:59], v[180:183], v[172:175], v[56:59]
	v_mfma_f32_16x16x32_bf16 v[40:43], v[184:187], v[156:159], v[40:43]
	v_mfma_f32_16x16x32_bf16 v[60:63], v[184:187], v[172:175], v[60:63]
	v_mfma_f32_16x16x32_bf16 v[44:47], v[196:199], v[156:159], v[44:47]
	v_mfma_f32_16x16x32_bf16 v[64:67], v[196:199], v[172:175], v[64:67]
	v_mfma_f32_16x16x32_bf16 v[48:51], v[200:203], v[156:159], v[48:51]
	v_mfma_f32_16x16x32_bf16 v[68:71], v[200:203], v[172:175], v[68:71]
	global_load_dwordx4 v[156:159], v1, s[8:9] offset:4032
	global_load_dwordx4 v[172:175], v1, s[16:17] offset:4032
	global_load_dwordx4 v[176:179], v1, s[18:19] offset:4032
	global_load_dwordx4 v[180:183], v1, s[28:29] offset:4032
	global_load_dwordx4 v[184:187], v1, s[30:31] offset:4032
	global_load_dwordx4 v[196:199], v1, s[34:35] offset:4032
	global_load_dwordx4 v[200:203], v1, s[36:37] offset:4032
	s_waitcnt vmcnt(28)
	v_mfma_f32_16x16x32_bf16 v[32:35], v[212:215], v[204:207], v[32:35]
	v_mfma_f32_16x16x32_bf16 v[52:55], v[212:215], v[208:211], v[52:55]
	v_mfma_f32_16x16x32_bf16 v[36:39], v[234:237], v[204:207], v[36:39]
	v_mfma_f32_16x16x32_bf16 v[56:59], v[234:237], v[208:211], v[56:59]
	v_mfma_f32_16x16x32_bf16 v[40:43], v[238:241], v[204:207], v[40:43]
	v_mfma_f32_16x16x32_bf16 v[60:63], v[238:241], v[208:211], v[60:63]
	v_mfma_f32_16x16x32_bf16 v[44:47], v[242:245], v[204:207], v[44:47]
	v_mfma_f32_16x16x32_bf16 v[64:67], v[242:245], v[208:211], v[64:67]
	v_mfma_f32_16x16x32_bf16 v[48:51], v[246:249], v[204:207], v[48:51]
	v_mfma_f32_16x16x32_bf16 v[68:71], v[246:249], v[208:211], v[68:71]
	s_waitcnt vmcnt(21)
	v_mfma_f32_16x16x32_bf16 v[32:35], v[80:83], v[72:75], v[32:35]
	v_mfma_f32_16x16x32_bf16 v[52:55], v[80:83], v[76:79], v[52:55]
	v_mfma_f32_16x16x32_bf16 v[36:39], v[84:87], v[72:75], v[36:39]
	v_mfma_f32_16x16x32_bf16 v[56:59], v[84:87], v[76:79], v[56:59]
	v_mfma_f32_16x16x32_bf16 v[40:43], v[88:91], v[72:75], v[40:43]
	v_mfma_f32_16x16x32_bf16 v[60:63], v[88:91], v[76:79], v[60:63]
	v_mfma_f32_16x16x32_bf16 v[44:47], v[92:95], v[72:75], v[44:47]
	v_mfma_f32_16x16x32_bf16 v[64:67], v[92:95], v[76:79], v[64:67]
	v_mfma_f32_16x16x32_bf16 v[48:51], v[96:99], v[72:75], v[48:51]
	v_mfma_f32_16x16x32_bf16 v[68:71], v[96:99], v[76:79], v[68:71]
	s_waitcnt vmcnt(14)
	v_mfma_f32_16x16x32_bf16 v[32:35], v[108:111], v[100:103], v[32:35]
	v_mfma_f32_16x16x32_bf16 v[52:55], v[108:111], v[104:107], v[52:55]
	v_mfma_f32_16x16x32_bf16 v[36:39], v[112:115], v[100:103], v[36:39]
	v_mfma_f32_16x16x32_bf16 v[56:59], v[112:115], v[104:107], v[56:59]
	v_mfma_f32_16x16x32_bf16 v[40:43], v[116:119], v[100:103], v[40:43]
	v_mfma_f32_16x16x32_bf16 v[60:63], v[116:119], v[104:107], v[60:63]
	v_mfma_f32_16x16x32_bf16 v[44:47], v[120:123], v[100:103], v[44:47]
	v_mfma_f32_16x16x32_bf16 v[64:67], v[120:123], v[104:107], v[64:67]
	v_mfma_f32_16x16x32_bf16 v[48:51], v[124:127], v[100:103], v[48:51]
	v_mfma_f32_16x16x32_bf16 v[68:71], v[124:127], v[104:107], v[68:71]
	s_waitcnt vmcnt(7)
	v_mfma_f32_16x16x32_bf16 v[32:35], v[136:139], v[128:131], v[32:35]
	v_mfma_f32_16x16x32_bf16 v[52:55], v[136:139], v[132:135], v[52:55]
	v_mfma_f32_16x16x32_bf16 v[36:39], v[140:143], v[128:131], v[36:39]
	v_mfma_f32_16x16x32_bf16 v[56:59], v[140:143], v[132:135], v[56:59]
	v_mfma_f32_16x16x32_bf16 v[40:43], v[144:147], v[128:131], v[40:43]
	v_mfma_f32_16x16x32_bf16 v[60:63], v[144:147], v[132:135], v[60:63]
	v_mfma_f32_16x16x32_bf16 v[44:47], v[148:151], v[128:131], v[44:47]
	v_mfma_f32_16x16x32_bf16 v[64:67], v[148:151], v[132:135], v[64:67]
	v_mfma_f32_16x16x32_bf16 v[48:51], v[152:155], v[128:131], v[48:51]
	v_mfma_f32_16x16x32_bf16 v[68:71], v[152:155], v[132:135], v[68:71]
	s_waitcnt vmcnt(0)
	v_mfma_f32_16x16x32_bf16 v[32:35], v[176:179], v[156:159], v[32:35]
	v_mfma_f32_16x16x32_bf16 v[52:55], v[176:179], v[172:175], v[52:55]
	v_mfma_f32_16x16x32_bf16 v[36:39], v[180:183], v[156:159], v[36:39]
	v_mfma_f32_16x16x32_bf16 v[56:59], v[180:183], v[172:175], v[56:59]
	v_mfma_f32_16x16x32_bf16 v[40:43], v[184:187], v[156:159], v[40:43]
	v_mfma_f32_16x16x32_bf16 v[60:63], v[184:187], v[172:175], v[60:63]
	v_mfma_f32_16x16x32_bf16 v[44:47], v[196:199], v[156:159], v[44:47]
	v_mfma_f32_16x16x32_bf16 v[64:67], v[196:199], v[172:175], v[64:67]
	v_mfma_f32_16x16x32_bf16 v[48:51], v[200:203], v[156:159], v[48:51]
	v_mfma_f32_16x16x32_bf16 v[68:71], v[200:203], v[172:175], v[68:71]
	global_load_dwordx4 v[72:75], v3, s[38:39]
	global_load_dwordx4 v[76:79], v3, s[38:39] offset:64
	global_load_dwordx4 v[80:83], v3, s[38:39] offset:128
	global_load_dwordx4 v[84:87], v3, s[38:39] offset:192
	global_load_dwordx4 v[88:91], v3, s[38:39] offset:256
	s_nop 7
	s_waitcnt vmcnt(0)
	v_add_f32_e32 v32, v32, v72
	v_add_f32_e32 v33, v33, v73
	v_add_f32_e32 v34, v34, v74
	v_add_f32_e32 v35, v35, v75
	v_add_f32_e32 v36, v36, v76
	v_add_f32_e32 v37, v37, v77
	v_add_f32_e32 v38, v38, v78
	v_add_f32_e32 v39, v39, v79
	v_add_f32_e32 v40, v40, v80
	v_add_f32_e32 v41, v41, v81
	v_add_f32_e32 v42, v42, v82
	v_add_f32_e32 v43, v43, v83
	v_add_f32_e32 v44, v44, v84
	v_add_f32_e32 v45, v45, v85
	v_add_f32_e32 v46, v46, v86
	v_add_f32_e32 v47, v47, v87
	v_add_f32_e32 v48, v48, v88
	v_add_f32_e32 v49, v49, v89
	v_add_f32_e32 v50, v50, v90
	v_add_f32_e32 v51, v51, v91
	v_add_f32_e32 v52, v52, v72
	v_add_f32_e32 v53, v53, v73
	v_add_f32_e32 v54, v54, v74
	v_add_f32_e32 v55, v55, v75
	v_add_f32_e32 v56, v56, v76
	v_add_f32_e32 v57, v57, v77
	v_add_f32_e32 v58, v58, v78
	v_add_f32_e32 v59, v59, v79
	v_add_f32_e32 v60, v60, v80
	v_add_f32_e32 v61, v61, v81
	v_add_f32_e32 v62, v62, v82
	v_add_f32_e32 v63, v63, v83
	v_add_f32_e32 v64, v64, v84
	v_add_f32_e32 v65, v65, v85
	v_add_f32_e32 v66, v66, v86
	v_add_f32_e32 v67, v67, v87
	v_add_f32_e32 v68, v68, v88
	v_add_f32_e32 v69, v69, v89
	v_add_f32_e32 v70, v70, v90
	v_add_f32_e32 v71, v71, v91
	s_nop 1
	global_store_dwordx4 v2, v[32:35], s[40:41]
	global_store_dwordx4 v2, v[36:39], s[40:41] offset:64
	global_store_dwordx4 v2, v[40:43], s[40:41] offset:128
	global_store_dwordx4 v2, v[44:47], s[40:41] offset:192
	global_store_dwordx4 v2, v[48:51], s[40:41] offset:256
	global_store_dwordx4 v2, v[52:55], s[46:47]
	global_store_dwordx4 v2, v[56:59], s[46:47] offset:64
	global_store_dwordx4 v2, v[60:63], s[46:47] offset:128
	global_store_dwordx4 v2, v[64:67], s[46:47] offset:192
	global_store_dwordx4 v2, v[68:71], s[46:47] offset:256
